# attention step: PV / row-sum MFMAs interleaved between the QK MFMAs so each K fragment LDS read has two MFMA slots to land
# speedup vs baseline: 1.0361x; 1.0057x over previous
.Lamla_loop:
	ds_read_b128 v[136:139], v243 offset:0
	ds_read_b128 v[140:143], v243 offset:6656
	ds_read_b128 v[144:147], v243 offset:32
	ds_read_b128 v[148:151], v243 offset:6688
	v_mfma_f32_32x32x16_bf16 v[0:15], v[176:179], v[96:99], v[0:15]
	v_max3_f32 v168, v64, v65, v66
	v_max3_f32 v170, v80, v81, v82
	v_max3_f32 v168, v168, v67, v68
	v_max3_f32 v170, v170, v83, v84
	v_max3_f32 v168, v168, v69, v70
	v_max3_f32 v170, v170, v85, v86
	s_mov_b32 s55, s52
	s_mov_b32 s52, s53
	s_mov_b32 s53, s54
	s_mov_b32 s54, s55
	s_mov_b32 s9, 0
	v_mfma_f32_32x32x16_bf16 v[16:31], v[180:183], v[96:99], v[16:31]
	v_max3_f32 v168, v168, v71, v72
	v_max3_f32 v170, v170, v87, v88
	v_max3_f32 v168, v168, v73, v74
	v_max3_f32 v170, v170, v89, v90
	v_max3_f32 v168, v168, v75, v76
	v_max3_f32 v170, v170, v91, v92
	global_load_dwordx4 v[152:155], v225, s[2:3]
	global_load_dwordx2 v[160:161], v165, s[10:11]
	global_load_dwordx4 v[156:159], v225, s[4:5]
	s_add_u32 s2, s2, 0x2000
	s_addc_u32 s3, s3, 0
	s_add_u32 s10, s10, 0x1000
	s_addc_u32 s11, s11, 0
	s_add_u32 s4, s4, 0x2000
	s_addc_u32 s5, s5, 0
	v_add_u32_e32 v222, s53, v220
	v_add_u32_e32 v224, s54, v221
	v_mfma_f32_32x32x16_bf16 v[226:241], v[246:249], v[96:99], v[226:241]
	v_max3_f32 v168, v168, v77, v78
	v_max3_f32 v170, v170, v93, v94
	v_max_f32_e32 v168, v168, v79
	v_max_f32_e32 v170, v170, v95
	v_max_f32_e32 v168, v168, v170
	s_waitcnt lgkmcnt(3)
	v_mfma_f32_32x32x16_bf16 v[32:47], v[136:139], v[112:115], 0
	v_mov_b32_e32 v170, v168
	s_nop 1
	v_permlane32_swap_b32_e32 v168, v170
	v_max_f32_e32 v168, v168, v170
	v_mul_f32_e32 v168, 0x3e16c740, v168
	v_cmp_gt_f32_e32 vcc, v168, v164
	s_cbranch_vccz .Lamla_nors_2
	v_max_f32_e32 v170, v162, v168
	v_sub_f32_e32 v166, v162, v170
	v_exp_f32_e32 v166, v166
	v_mov_b32_e32 v162, v170
	v_add_f32_e32 v164, 0x41000000, v170
	v_xor_b32_e32 v163, 0x80000000, v170
	s_mov_b32 s9, 1
.Lamla_nors_2:
	ds_read_b128 v[136:139], v243 offset:64
	ds_read_b64_tr_b16 v[192:193], v223 offset:3072
	ds_read_b64_tr_b16 v[194:195], v223 offset:4608
	s_waitcnt lgkmcnt(5)
	v_mfma_f32_32x32x16_bf16 v[48:63], v[140:143], v[112:115], 0
	v_fmamk_f32 v64, v64, 0x3e16c740, v163
	v_fmamk_f32 v80, v80, 0x3e16c740, v163
	v_exp_f32_e32 v64, v64
	v_exp_f32_e32 v80, v80
	ds_read_b128 v[140:143], v243 offset:6720
	ds_read_b64_tr_b16 v[196:197], v223 offset:3136
	ds_read_b64_tr_b16 v[198:199], v223 offset:4672
	v_mfma_f32_32x32x16_bf16 v[0:15], v[184:187], v[104:107], v[0:15]
	v_fmamk_f32 v65, v65, 0x3e16c740, v163
	v_fmamk_f32 v81, v81, 0x3e16c740, v163
	v_exp_f32_e32 v65, v65
	v_exp_f32_e32 v81, v81
	ds_read_b64_tr_b16 v[200:201], v223 offset:9216
	ds_read_b64_tr_b16 v[202:203], v223 offset:10752
	s_waitcnt lgkmcnt(9)
	v_mfma_f32_32x32x16_bf16 v[32:47], v[144:147], v[116:119], v[32:47]
	v_fmamk_f32 v66, v66, 0x3e16c740, v163
	v_fmamk_f32 v82, v82, 0x3e16c740, v163
	v_exp_f32_e32 v66, v66
	v_exp_f32_e32 v82, v82
	ds_read_b128 v[144:147], v243 offset:96
	ds_read_b64_tr_b16 v[204:205], v223 offset:9280
	ds_read_b64_tr_b16 v[206:207], v223 offset:10816
	v_mfma_f32_32x32x16_bf16 v[16:31], v[188:191], v[104:107], v[16:31]
	v_cvt_pk_bf16_f32 v96, v64, v65
	v_fmamk_f32 v67, v67, 0x3e16c740, v163
	v_fmamk_f32 v83, v83, 0x3e16c740, v163
	v_exp_f32_e32 v67, v67
	s_waitcnt lgkmcnt(11)
	v_mfma_f32_32x32x16_bf16 v[48:63], v[148:151], v[116:119], v[48:63]
	v_exp_f32_e32 v83, v83
	v_fmamk_f32 v68, v68, 0x3e16c740, v163
	v_fmamk_f32 v84, v84, 0x3e16c740, v163
	v_exp_f32_e32 v68, v68
	ds_read_b128 v[148:151], v243 offset:6752
	v_mfma_f32_32x32x16_bf16 v[226:241], v[246:249], v[104:107], v[226:241]
	v_cvt_pk_bf16_f32 v104, v80, v81
	v_exp_f32_e32 v84, v84
	v_cvt_pk_bf16_f32 v97, v66, v67
	v_cvt_pk_bf16_f32 v105, v82, v83
	v_fmamk_f32 v69, v69, 0x3e16c740, v163
	s_waitcnt lgkmcnt(11)
	v_mfma_f32_32x32x16_bf16 v[32:47], v[136:139], v[120:123], v[32:47]
	v_fmamk_f32 v85, v85, 0x3e16c740, v163
	v_exp_f32_e32 v69, v69
	v_exp_f32_e32 v85, v85
	ds_read_b128 v[136:139], v243 offset:128
	s_waitcnt lgkmcnt(9)
	v_mfma_f32_32x32x16_bf16 v[48:63], v[140:143], v[120:123], v[48:63]
	v_fmamk_f32 v70, v70, 0x3e16c740, v163
	v_fmamk_f32 v86, v86, 0x3e16c740, v163
	v_exp_f32_e32 v70, v70
	v_exp_f32_e32 v86, v86
	ds_read_b128 v[140:143], v243 offset:6784
	v_mfma_f32_32x32x16_bf16 v[0:15], v[192:195], v[100:103], v[0:15]
	v_cvt_pk_bf16_f32 v98, v68, v69
	v_cvt_pk_bf16_f32 v106, v84, v85
	v_fmamk_f32 v71, v71, 0x3e16c740, v163
	v_fmamk_f32 v87, v87, 0x3e16c740, v163
	v_exp_f32_e32 v71, v71
	s_waitcnt lgkmcnt(5)
	v_mfma_f32_32x32x16_bf16 v[32:47], v[144:147], v[124:127], v[32:47]
	v_exp_f32_e32 v87, v87
	v_fmamk_f32 v72, v72, 0x3e16c740, v163
	v_fmamk_f32 v88, v88, 0x3e16c740, v163
	v_exp_f32_e32 v72, v72
	ds_read_b128 v[144:147], v243 offset:160
	v_mfma_f32_32x32x16_bf16 v[16:31], v[196:199], v[100:103], v[16:31]
	v_exp_f32_e32 v88, v88
	v_cvt_pk_bf16_f32 v99, v70, v71
	v_cvt_pk_bf16_f32 v107, v86, v87
	v_fmamk_f32 v73, v73, 0x3e16c740, v163
	s_waitcnt vmcnt(5)
	ds_write_b128 v218, v[208:211] offset:13312
	s_waitcnt vmcnt(4)
	ds_write_b64 v219, v[216:217] offset:13312
	s_waitcnt vmcnt(3)
	ds_write_b128 v224, v[212:215]
	s_waitcnt lgkmcnt(6)
	v_mfma_f32_32x32x16_bf16 v[48:63], v[148:151], v[124:127], v[48:63]
	v_fmamk_f32 v89, v89, 0x3e16c740, v163
	v_exp_f32_e32 v73, v73
	v_exp_f32_e32 v89, v89
	ds_read_b128 v[148:151], v243 offset:6816
	v_mfma_f32_32x32x16_bf16 v[226:241], v[246:249], v[100:103], v[226:241]
	v_fmamk_f32 v74, v74, 0x3e16c740, v163
	v_fmamk_f32 v90, v90, 0x3e16c740, v163
	v_exp_f32_e32 v74, v74
	v_exp_f32_e32 v90, v90
	s_waitcnt lgkmcnt(6)
	v_mfma_f32_32x32x16_bf16 v[32:47], v[136:139], v[128:131], v[32:47]
	v_cvt_pk_bf16_f32 v100, v72, v73
	v_fmamk_f32 v75, v75, 0x3e16c740, v163
	v_fmamk_f32 v91, v91, 0x3e16c740, v163
	v_exp_f32_e32 v75, v75
	v_exp_f32_e32 v91, v91
	s_waitcnt lgkmcnt(5)
	v_mfma_f32_32x32x16_bf16 v[48:63], v[140:143], v[128:131], v[48:63]
	v_fmamk_f32 v76, v76, 0x3e16c740, v163
	v_fmamk_f32 v92, v92, 0x3e16c740, v163
	v_exp_f32_e32 v76, v76
	ds_read_b64_tr_b16 v[176:177], v222 offset:0
	ds_read_b64_tr_b16 v[178:179], v222 offset:1536
	v_mfma_f32_32x32x16_bf16 v[0:15], v[200:203], v[108:111], v[0:15]
	v_exp_f32_e32 v92, v92
	v_cvt_pk_bf16_f32 v101, v74, v75
	v_fmamk_f32 v77, v77, 0x3e16c740, v163
	v_fmamk_f32 v93, v93, 0x3e16c740, v163
	v_exp_f32_e32 v77, v77
	ds_read_b64_tr_b16 v[180:181], v222 offset:64
	ds_read_b64_tr_b16 v[182:183], v222 offset:1600
	s_waitcnt lgkmcnt(8)
	v_mfma_f32_32x32x16_bf16 v[32:47], v[144:147], v[132:135], v[32:47]
	v_exp_f32_e32 v93, v93
	v_fmamk_f32 v78, v78, 0x3e16c740, v163
	v_fmamk_f32 v94, v94, 0x3e16c740, v163
	v_exp_f32_e32 v78, v78
	ds_read_b64_tr_b16 v[184:185], v222 offset:6144
	ds_read_b64_tr_b16 v[186:187], v222 offset:7680
	v_mfma_f32_32x32x16_bf16 v[16:31], v[204:207], v[108:111], v[16:31]
	v_exp_f32_e32 v94, v94
	v_cvt_pk_bf16_f32 v102, v76, v77
	v_fmamk_f32 v79, v79, 0x3e16c740, v163
	ds_read_b64_tr_b16 v[188:189], v222 offset:6208
	ds_read_b64_tr_b16 v[190:191], v222 offset:7744
	s_waitcnt lgkmcnt(8)
	v_mfma_f32_32x32x16_bf16 v[48:63], v[148:151], v[132:135], v[48:63]
	v_fmamk_f32 v95, v95, 0x3e16c740, v163
	v_exp_f32_e32 v79, v79
	v_exp_f32_e32 v95, v95
	v_cvt_pk_bf16_f32 v103, v78, v79
	v_mfma_f32_32x32x16_bf16 v[226:241], v[246:249], v[108:111], v[226:241]
	v_cvt_pk_bf16_f32 v108, v88, v89
	v_cvt_pk_bf16_f32 v109, v90, v91
	v_cvt_pk_bf16_f32 v110, v92, v93
	v_cvt_pk_bf16_f32 v111, v94, v95
	s_cmp_lg_u32 s9, 0
	s_cbranch_scc0 .Lamla_noresc_3
	s_nop 15
	v_pk_mul_f32 v[0:1], v[0:1], v[166:167] op_sel_hi:[1,0]
	v_pk_mul_f32 v[2:3], v[2:3], v[166:167] op_sel_hi:[1,0]
	v_pk_mul_f32 v[4:5], v[4:5], v[166:167] op_sel_hi:[1,0]
	v_pk_mul_f32 v[6:7], v[6:7], v[166:167] op_sel_hi:[1,0]
	v_pk_mul_f32 v[8:9], v[8:9], v[166:167] op_sel_hi:[1,0]
	v_pk_mul_f32 v[10:11], v[10:11], v[166:167] op_sel_hi:[1,0]
	v_pk_mul_f32 v[12:13], v[12:13], v[166:167] op_sel_hi:[1,0]
	v_pk_mul_f32 v[14:15], v[14:15], v[166:167] op_sel_hi:[1,0]
	v_pk_mul_f32 v[16:17], v[16:17], v[166:167] op_sel_hi:[1,0]
	v_pk_mul_f32 v[18:19], v[18:19], v[166:167] op_sel_hi:[1,0]
	v_pk_mul_f32 v[20:21], v[20:21], v[166:167] op_sel_hi:[1,0]
	v_pk_mul_f32 v[22:23], v[22:23], v[166:167] op_sel_hi:[1,0]
	v_pk_mul_f32 v[24:25], v[24:25], v[166:167] op_sel_hi:[1,0]
	v_pk_mul_f32 v[26:27], v[26:27], v[166:167] op_sel_hi:[1,0]
	v_pk_mul_f32 v[28:29], v[28:29], v[166:167] op_sel_hi:[1,0]
	v_pk_mul_f32 v[30:31], v[30:31], v[166:167] op_sel_hi:[1,0]
	v_mul_f32_e32 v226, v226, v166
.Lamla_noresc_3:
	s_waitcnt lgkmcnt(0)
	s_barrier
	ds_read_b128 v[136:139], v243 offset:13312
	ds_read_b128 v[140:143], v243 offset:19968
	ds_read_b128 v[144:147], v243 offset:13344
	ds_read_b128 v[148:151], v243 offset:20000
	v_mfma_f32_32x32x16_bf16 v[0:15], v[176:179], v[96:99], v[0:15]
	v_max3_f32 v168, v32, v33, v34
	v_max3_f32 v170, v48, v49, v50
	v_max3_f32 v168, v168, v35, v36
	v_max3_f32 v170, v170, v51, v52
	v_max3_f32 v168, v168, v37, v38
	v_max3_f32 v170, v170, v53, v54
	s_mov_b32 s55, s52
	s_mov_b32 s52, s53
	s_mov_b32 s53, s54
	s_mov_b32 s54, s55
	s_mov_b32 s9, 0
	v_mfma_f32_32x32x16_bf16 v[16:31], v[180:183], v[96:99], v[16:31]
	v_max3_f32 v168, v168, v39, v40
	v_max3_f32 v170, v170, v55, v56
	v_max3_f32 v168, v168, v41, v42
	v_max3_f32 v170, v170, v57, v58
	v_max3_f32 v168, v168, v43, v44
	v_max3_f32 v170, v170, v59, v60
	global_load_dwordx4 v[208:211], v225, s[2:3]
	global_load_dwordx2 v[216:217], v165, s[10:11]
	global_load_dwordx4 v[212:215], v225, s[4:5]
	s_add_u32 s2, s2, 0x2000
	s_addc_u32 s3, s3, 0
	s_add_u32 s10, s10, 0x1000
	s_addc_u32 s11, s11, 0
	s_add_u32 s4, s4, 0x2000
	s_addc_u32 s5, s5, 0
	v_add_u32_e32 v223, s53, v220
	v_add_u32_e32 v224, s54, v221
	v_mfma_f32_32x32x16_bf16 v[226:241], v[246:249], v[96:99], v[226:241]
	v_max3_f32 v168, v168, v45, v46
	v_max3_f32 v170, v170, v61, v62
	v_max_f32_e32 v168, v168, v47
	v_max_f32_e32 v170, v170, v63
	v_max_f32_e32 v168, v168, v170
	s_waitcnt lgkmcnt(3)
	v_mfma_f32_32x32x16_bf16 v[64:79], v[136:139], v[112:115], 0
	v_mov_b32_e32 v170, v168
	s_nop 1
	v_permlane32_swap_b32_e32 v168, v170
	v_max_f32_e32 v168, v168, v170
	v_mul_f32_e32 v168, 0x3e16c740, v168
	v_cmp_gt_f32_e32 vcc, v168, v164
	s_cbranch_vccz .Lamla_nors_4
	v_max_f32_e32 v170, v162, v168
	v_sub_f32_e32 v166, v162, v170
	v_exp_f32_e32 v166, v166
	v_mov_b32_e32 v162, v170
	v_add_f32_e32 v164, 0x41000000, v170
	v_xor_b32_e32 v163, 0x80000000, v170
	s_mov_b32 s9, 1
.Lamla_nors_4:
	ds_read_b128 v[136:139], v243 offset:13376
	ds_read_b64_tr_b16 v[192:193], v222 offset:3072
	ds_read_b64_tr_b16 v[194:195], v222 offset:4608
	s_waitcnt lgkmcnt(5)
	v_mfma_f32_32x32x16_bf16 v[80:95], v[140:143], v[112:115], 0
	v_fmamk_f32 v32, v32, 0x3e16c740, v163
	v_fmamk_f32 v48, v48, 0x3e16c740, v163
	v_exp_f32_e32 v32, v32
	v_exp_f32_e32 v48, v48
	ds_read_b128 v[140:143], v243 offset:20032
	ds_read_b64_tr_b16 v[196:197], v222 offset:3136
	ds_read_b64_tr_b16 v[198:199], v222 offset:4672
	v_mfma_f32_32x32x16_bf16 v[0:15], v[184:187], v[104:107], v[0:15]
	v_fmamk_f32 v33, v33, 0x3e16c740, v163
	v_fmamk_f32 v49, v49, 0x3e16c740, v163
	v_exp_f32_e32 v33, v33
	v_exp_f32_e32 v49, v49
	ds_read_b64_tr_b16 v[200:201], v222 offset:9216
	ds_read_b64_tr_b16 v[202:203], v222 offset:10752
	s_waitcnt lgkmcnt(9)
	v_mfma_f32_32x32x16_bf16 v[64:79], v[144:147], v[116:119], v[64:79]
	v_fmamk_f32 v34, v34, 0x3e16c740, v163
	v_fmamk_f32 v50, v50, 0x3e16c740, v163
	v_exp_f32_e32 v34, v34
	v_exp_f32_e32 v50, v50
	ds_read_b128 v[144:147], v243 offset:13408
	ds_read_b64_tr_b16 v[204:205], v222 offset:9280
	ds_read_b64_tr_b16 v[206:207], v222 offset:10816
	v_mfma_f32_32x32x16_bf16 v[16:31], v[188:191], v[104:107], v[16:31]
	v_cvt_pk_bf16_f32 v96, v32, v33
	v_fmamk_f32 v35, v35, 0x3e16c740, v163
	v_fmamk_f32 v51, v51, 0x3e16c740, v163
	v_exp_f32_e32 v35, v35
	s_waitcnt lgkmcnt(11)
	v_mfma_f32_32x32x16_bf16 v[80:95], v[148:151], v[116:119], v[80:95]
	v_exp_f32_e32 v51, v51
	v_fmamk_f32 v36, v36, 0x3e16c740, v163
	v_fmamk_f32 v52, v52, 0x3e16c740, v163
	v_exp_f32_e32 v36, v36
	ds_read_b128 v[148:151], v243 offset:20064
	v_mfma_f32_32x32x16_bf16 v[226:241], v[246:249], v[104:107], v[226:241]
	v_cvt_pk_bf16_f32 v104, v48, v49
	v_exp_f32_e32 v52, v52
	v_cvt_pk_bf16_f32 v97, v34, v35
	v_cvt_pk_bf16_f32 v105, v50, v51
	v_fmamk_f32 v37, v37, 0x3e16c740, v163
	s_waitcnt lgkmcnt(11)
	v_mfma_f32_32x32x16_bf16 v[64:79], v[136:139], v[120:123], v[64:79]
	v_fmamk_f32 v53, v53, 0x3e16c740, v163
	v_exp_f32_e32 v37, v37
	v_exp_f32_e32 v53, v53
	ds_read_b128 v[136:139], v243 offset:13440
	s_waitcnt lgkmcnt(9)
	v_mfma_f32_32x32x16_bf16 v[80:95], v[140:143], v[120:123], v[80:95]
	v_fmamk_f32 v38, v38, 0x3e16c740, v163
	v_fmamk_f32 v54, v54, 0x3e16c740, v163
	v_exp_f32_e32 v38, v38
	v_exp_f32_e32 v54, v54
	ds_read_b128 v[140:143], v243 offset:20096
	v_mfma_f32_32x32x16_bf16 v[0:15], v[192:195], v[100:103], v[0:15]
	v_cvt_pk_bf16_f32 v98, v36, v37
	v_cvt_pk_bf16_f32 v106, v52, v53
	v_fmamk_f32 v39, v39, 0x3e16c740, v163
	v_fmamk_f32 v55, v55, 0x3e16c740, v163
	v_exp_f32_e32 v39, v39
	s_waitcnt lgkmcnt(5)
	v_mfma_f32_32x32x16_bf16 v[64:79], v[144:147], v[124:127], v[64:79]
	v_exp_f32_e32 v55, v55
	v_fmamk_f32 v40, v40, 0x3e16c740, v163
	v_fmamk_f32 v56, v56, 0x3e16c740, v163
	v_exp_f32_e32 v40, v40
	ds_read_b128 v[144:147], v243 offset:13472
	v_mfma_f32_32x32x16_bf16 v[16:31], v[196:199], v[100:103], v[16:31]
	v_exp_f32_e32 v56, v56
	v_cvt_pk_bf16_f32 v99, v38, v39
	v_cvt_pk_bf16_f32 v107, v54, v55
	v_fmamk_f32 v41, v41, 0x3e16c740, v163
	s_waitcnt vmcnt(5)
	ds_write_b128 v218, v[152:155]
	s_waitcnt vmcnt(4)
	ds_write_b64 v219, v[160:161]
	s_waitcnt vmcnt(3)
	ds_write_b128 v224, v[156:159]
	s_waitcnt lgkmcnt(6)
	v_mfma_f32_32x32x16_bf16 v[80:95], v[148:151], v[124:127], v[80:95]
	v_fmamk_f32 v57, v57, 0x3e16c740, v163
	v_exp_f32_e32 v41, v41
	v_exp_f32_e32 v57, v57
	ds_read_b128 v[148:151], v243 offset:20128
	v_mfma_f32_32x32x16_bf16 v[226:241], v[246:249], v[100:103], v[226:241]
	v_fmamk_f32 v42, v42, 0x3e16c740, v163
	v_fmamk_f32 v58, v58, 0x3e16c740, v163
	v_exp_f32_e32 v42, v42
	v_exp_f32_e32 v58, v58
	s_waitcnt lgkmcnt(6)
	v_mfma_f32_32x32x16_bf16 v[64:79], v[136:139], v[128:131], v[64:79]
	v_cvt_pk_bf16_f32 v100, v40, v41
	v_fmamk_f32 v43, v43, 0x3e16c740, v163
	v_fmamk_f32 v59, v59, 0x3e16c740, v163
	v_exp_f32_e32 v43, v43
	v_exp_f32_e32 v59, v59
	s_waitcnt lgkmcnt(5)
	v_mfma_f32_32x32x16_bf16 v[80:95], v[140:143], v[128:131], v[80:95]
	v_fmamk_f32 v44, v44, 0x3e16c740, v163
	v_fmamk_f32 v60, v60, 0x3e16c740, v163
	v_exp_f32_e32 v44, v44
	ds_read_b64_tr_b16 v[176:177], v223 offset:0
	ds_read_b64_tr_b16 v[178:179], v223 offset:1536
	v_mfma_f32_32x32x16_bf16 v[0:15], v[200:203], v[108:111], v[0:15]
	v_exp_f32_e32 v60, v60
	v_cvt_pk_bf16_f32 v101, v42, v43
	v_fmamk_f32 v45, v45, 0x3e16c740, v163
	v_fmamk_f32 v61, v61, 0x3e16c740, v163
	v_exp_f32_e32 v45, v45
	ds_read_b64_tr_b16 v[180:181], v223 offset:64
	ds_read_b64_tr_b16 v[182:183], v223 offset:1600
	s_waitcnt lgkmcnt(8)
	v_mfma_f32_32x32x16_bf16 v[64:79], v[144:147], v[132:135], v[64:79]
	v_exp_f32_e32 v61, v61
	v_fmamk_f32 v46, v46, 0x3e16c740, v163
	v_fmamk_f32 v62, v62, 0x3e16c740, v163
	v_exp_f32_e32 v46, v46
	ds_read_b64_tr_b16 v[184:185], v223 offset:6144
	ds_read_b64_tr_b16 v[186:187], v223 offset:7680
	v_mfma_f32_32x32x16_bf16 v[16:31], v[204:207], v[108:111], v[16:31]
	v_exp_f32_e32 v62, v62
	v_cvt_pk_bf16_f32 v102, v44, v45
	v_fmamk_f32 v47, v47, 0x3e16c740, v163
	ds_read_b64_tr_b16 v[188:189], v223 offset:6208
	ds_read_b64_tr_b16 v[190:191], v223 offset:7744
	s_waitcnt lgkmcnt(8)
	v_mfma_f32_32x32x16_bf16 v[80:95], v[148:151], v[132:135], v[80:95]
	v_fmamk_f32 v63, v63, 0x3e16c740, v163
	v_exp_f32_e32 v47, v47
	v_exp_f32_e32 v63, v63
	v_cvt_pk_bf16_f32 v103, v46, v47
	v_mfma_f32_32x32x16_bf16 v[226:241], v[246:249], v[108:111], v[226:241]
	v_cvt_pk_bf16_f32 v108, v56, v57
	v_cvt_pk_bf16_f32 v109, v58, v59
	v_cvt_pk_bf16_f32 v110, v60, v61
	v_cvt_pk_bf16_f32 v111, v62, v63
	s_cmp_lg_u32 s9, 0
	s_cbranch_scc0 .Lamla_noresc_5
	s_nop 15
	v_pk_mul_f32 v[0:1], v[0:1], v[166:167] op_sel_hi:[1,0]
	v_pk_mul_f32 v[2:3], v[2:3], v[166:167] op_sel_hi:[1,0]
	v_pk_mul_f32 v[4:5], v[4:5], v[166:167] op_sel_hi:[1,0]
	v_pk_mul_f32 v[6:7], v[6:7], v[166:167] op_sel_hi:[1,0]
	v_pk_mul_f32 v[8:9], v[8:9], v[166:167] op_sel_hi:[1,0]
	v_pk_mul_f32 v[10:11], v[10:11], v[166:167] op_sel_hi:[1,0]
	v_pk_mul_f32 v[12:13], v[12:13], v[166:167] op_sel_hi:[1,0]
	v_pk_mul_f32 v[14:15], v[14:15], v[166:167] op_sel_hi:[1,0]
	v_pk_mul_f32 v[16:17], v[16:17], v[166:167] op_sel_hi:[1,0]
	v_pk_mul_f32 v[18:19], v[18:19], v[166:167] op_sel_hi:[1,0]
	v_pk_mul_f32 v[20:21], v[20:21], v[166:167] op_sel_hi:[1,0]
	v_pk_mul_f32 v[22:23], v[22:23], v[166:167] op_sel_hi:[1,0]
	v_pk_mul_f32 v[24:25], v[24:25], v[166:167] op_sel_hi:[1,0]
	v_pk_mul_f32 v[26:27], v[26:27], v[166:167] op_sel_hi:[1,0]
	v_pk_mul_f32 v[28:29], v[28:29], v[166:167] op_sel_hi:[1,0]
	v_pk_mul_f32 v[30:31], v[30:31], v[166:167] op_sel_hi:[1,0]
	v_mul_f32_e32 v226, v226, v166

.Lamla_tail:
	ds_read_b128 v[136:139], v243 offset:0
	ds_read_b128 v[140:143], v243 offset:6656
	ds_read_b128 v[144:147], v243 offset:32
	ds_read_b128 v[148:151], v243 offset:6688
	v_mfma_f32_32x32x16_bf16 v[0:15], v[176:179], v[96:99], v[0:15]
	v_max3_f32 v168, v64, v65, v66
	v_max3_f32 v170, v80, v81, v82
	v_max3_f32 v168, v168, v67, v68
	v_max3_f32 v170, v170, v83, v84
	v_max3_f32 v168, v168, v69, v70
	v_max3_f32 v170, v170, v85, v86
	s_mov_b32 s55, s52
	s_mov_b32 s52, s53
	s_mov_b32 s53, s54
	s_mov_b32 s54, s55
	s_mov_b32 s9, 0
	v_mfma_f32_32x32x16_bf16 v[16:31], v[180:183], v[96:99], v[16:31]
	v_max3_f32 v168, v168, v71, v72
	v_max3_f32 v170, v170, v87, v88
	v_max3_f32 v168, v168, v73, v74
	v_max3_f32 v170, v170, v89, v90
	v_max3_f32 v168, v168, v75, v76
	v_max3_f32 v170, v170, v91, v92
	global_load_dwordx4 v[156:159], v225, s[4:5]
	s_add_u32 s4, s4, 0x2000
	s_addc_u32 s5, s5, 0
	v_add_u32_e32 v222, s53, v220
	v_add_u32_e32 v224, s54, v221
	v_mfma_f32_32x32x16_bf16 v[226:241], v[246:249], v[96:99], v[226:241]
	v_max3_f32 v168, v168, v77, v78
	v_max3_f32 v170, v170, v93, v94
	v_max_f32_e32 v168, v168, v79
	v_max_f32_e32 v170, v170, v95
	v_max_f32_e32 v168, v168, v170
	s_waitcnt lgkmcnt(3)
	v_mfma_f32_32x32x16_bf16 v[32:47], v[136:139], v[112:115], 0
	v_mov_b32_e32 v170, v168
	s_nop 1
	v_permlane32_swap_b32_e32 v168, v170
	v_max_f32_e32 v168, v168, v170
	v_mul_f32_e32 v168, 0x3e16c740, v168
	v_cmp_gt_f32_e32 vcc, v168, v164
	s_cbranch_vccz .Lamla_nors_6
	v_max_f32_e32 v170, v162, v168
	v_sub_f32_e32 v166, v162, v170
	v_exp_f32_e32 v166, v166
	v_mov_b32_e32 v162, v170
	v_add_f32_e32 v164, 0x41000000, v170
	v_xor_b32_e32 v163, 0x80000000, v170
	s_mov_b32 s9, 1
.Lamla_nors_6:
	ds_read_b128 v[136:139], v243 offset:64
	ds_read_b64_tr_b16 v[192:193], v223 offset:3072
	ds_read_b64_tr_b16 v[194:195], v223 offset:4608
	s_waitcnt lgkmcnt(5)
	v_mfma_f32_32x32x16_bf16 v[48:63], v[140:143], v[112:115], 0
	v_fmamk_f32 v64, v64, 0x3e16c740, v163
	v_fmamk_f32 v80, v80, 0x3e16c740, v163
	v_exp_f32_e32 v64, v64
	v_exp_f32_e32 v80, v80
	ds_read_b128 v[140:143], v243 offset:6720
	ds_read_b64_tr_b16 v[196:197], v223 offset:3136
	ds_read_b64_tr_b16 v[198:199], v223 offset:4672
	v_mfma_f32_32x32x16_bf16 v[0:15], v[184:187], v[104:107], v[0:15]
	v_fmamk_f32 v65, v65, 0x3e16c740, v163
	v_fmamk_f32 v81, v81, 0x3e16c740, v163
	v_exp_f32_e32 v65, v65
	v_exp_f32_e32 v81, v81
	ds_read_b64_tr_b16 v[200:201], v223 offset:9216
	ds_read_b64_tr_b16 v[202:203], v223 offset:10752
	s_waitcnt lgkmcnt(9)
	v_mfma_f32_32x32x16_bf16 v[32:47], v[144:147], v[116:119], v[32:47]
	v_fmamk_f32 v66, v66, 0x3e16c740, v163
	v_fmamk_f32 v82, v82, 0x3e16c740, v163
	v_exp_f32_e32 v66, v66
	v_exp_f32_e32 v82, v82
	ds_read_b128 v[144:147], v243 offset:96
	ds_read_b64_tr_b16 v[204:205], v223 offset:9280
	ds_read_b64_tr_b16 v[206:207], v223 offset:10816
	v_mfma_f32_32x32x16_bf16 v[16:31], v[188:191], v[104:107], v[16:31]
	v_cvt_pk_bf16_f32 v96, v64, v65
	v_fmamk_f32 v67, v67, 0x3e16c740, v163
	v_fmamk_f32 v83, v83, 0x3e16c740, v163
	v_exp_f32_e32 v67, v67
	s_waitcnt lgkmcnt(11)
	v_mfma_f32_32x32x16_bf16 v[48:63], v[148:151], v[116:119], v[48:63]
	v_exp_f32_e32 v83, v83
	v_fmamk_f32 v68, v68, 0x3e16c740, v163
	v_fmamk_f32 v84, v84, 0x3e16c740, v163
	v_exp_f32_e32 v68, v68
	ds_read_b128 v[148:151], v243 offset:6752
	v_mfma_f32_32x32x16_bf16 v[226:241], v[246:249], v[104:107], v[226:241]
	v_cvt_pk_bf16_f32 v104, v80, v81
	v_exp_f32_e32 v84, v84
	v_cvt_pk_bf16_f32 v97, v66, v67
	v_cvt_pk_bf16_f32 v105, v82, v83
	v_fmamk_f32 v69, v69, 0x3e16c740, v163
	s_waitcnt lgkmcnt(11)
	v_mfma_f32_32x32x16_bf16 v[32:47], v[136:139], v[120:123], v[32:47]
	v_fmamk_f32 v85, v85, 0x3e16c740, v163
	v_exp_f32_e32 v69, v69
	v_exp_f32_e32 v85, v85
	ds_read_b128 v[136:139], v243 offset:128
	s_waitcnt lgkmcnt(9)
	v_mfma_f32_32x32x16_bf16 v[48:63], v[140:143], v[120:123], v[48:63]
	v_fmamk_f32 v70, v70, 0x3e16c740, v163
	v_fmamk_f32 v86, v86, 0x3e16c740, v163
	v_exp_f32_e32 v70, v70
	v_exp_f32_e32 v86, v86
	ds_read_b128 v[140:143], v243 offset:6784
	v_mfma_f32_32x32x16_bf16 v[0:15], v[192:195], v[100:103], v[0:15]
	v_cvt_pk_bf16_f32 v98, v68, v69
	v_cvt_pk_bf16_f32 v106, v84, v85
	v_fmamk_f32 v71, v71, 0x3e16c740, v163
	v_fmamk_f32 v87, v87, 0x3e16c740, v163
	v_exp_f32_e32 v71, v71
	s_waitcnt lgkmcnt(5)
	v_mfma_f32_32x32x16_bf16 v[32:47], v[144:147], v[124:127], v[32:47]
	v_exp_f32_e32 v87, v87
	v_fmamk_f32 v72, v72, 0x3e16c740, v163
	v_fmamk_f32 v88, v88, 0x3e16c740, v163
	v_exp_f32_e32 v72, v72
	ds_read_b128 v[144:147], v243 offset:160
	v_mfma_f32_32x32x16_bf16 v[16:31], v[196:199], v[100:103], v[16:31]
	v_exp_f32_e32 v88, v88
	v_cvt_pk_bf16_f32 v99, v70, v71
	v_cvt_pk_bf16_f32 v107, v86, v87
	v_fmamk_f32 v73, v73, 0x3e16c740, v163
	s_waitcnt vmcnt(3)
	ds_write_b128 v218, v[208:211] offset:13312
	s_waitcnt vmcnt(2)
	ds_write_b64 v219, v[216:217] offset:13312
	s_waitcnt vmcnt(1)
	ds_write_b128 v224, v[212:215]
	s_waitcnt lgkmcnt(6)
	v_mfma_f32_32x32x16_bf16 v[48:63], v[148:151], v[124:127], v[48:63]
	v_fmamk_f32 v89, v89, 0x3e16c740, v163
	v_exp_f32_e32 v73, v73
	v_exp_f32_e32 v89, v89
	ds_read_b128 v[148:151], v243 offset:6816
	v_mfma_f32_32x32x16_bf16 v[226:241], v[246:249], v[100:103], v[226:241]
	v_fmamk_f32 v74, v74, 0x3e16c740, v163
	v_fmamk_f32 v90, v90, 0x3e16c740, v163
	v_exp_f32_e32 v74, v74
	v_exp_f32_e32 v90, v90
	s_waitcnt lgkmcnt(6)
	v_mfma_f32_32x32x16_bf16 v[32:47], v[136:139], v[128:131], v[32:47]
	v_cvt_pk_bf16_f32 v100, v72, v73
	v_fmamk_f32 v75, v75, 0x3e16c740, v163
	v_fmamk_f32 v91, v91, 0x3e16c740, v163
	v_exp_f32_e32 v75, v75
	v_exp_f32_e32 v91, v91
	s_waitcnt lgkmcnt(5)
	v_mfma_f32_32x32x16_bf16 v[48:63], v[140:143], v[128:131], v[48:63]
	v_fmamk_f32 v76, v76, 0x3e16c740, v163
	v_fmamk_f32 v92, v92, 0x3e16c740, v163
	v_exp_f32_e32 v76, v76
	ds_read_b64_tr_b16 v[176:177], v222 offset:0
	ds_read_b64_tr_b16 v[178:179], v222 offset:1536
	v_mfma_f32_32x32x16_bf16 v[0:15], v[200:203], v[108:111], v[0:15]
	v_exp_f32_e32 v92, v92
	v_cvt_pk_bf16_f32 v101, v74, v75
	v_fmamk_f32 v77, v77, 0x3e16c740, v163
	v_fmamk_f32 v93, v93, 0x3e16c740, v163
	v_exp_f32_e32 v77, v77
	ds_read_b64_tr_b16 v[180:181], v222 offset:64
	ds_read_b64_tr_b16 v[182:183], v222 offset:1600
	s_waitcnt lgkmcnt(8)
	v_mfma_f32_32x32x16_bf16 v[32:47], v[144:147], v[132:135], v[32:47]
	v_exp_f32_e32 v93, v93
	v_fmamk_f32 v78, v78, 0x3e16c740, v163
	v_fmamk_f32 v94, v94, 0x3e16c740, v163
	v_exp_f32_e32 v78, v78
	ds_read_b64_tr_b16 v[184:185], v222 offset:6144
	ds_read_b64_tr_b16 v[186:187], v222 offset:7680
	v_mfma_f32_32x32x16_bf16 v[16:31], v[204:207], v[108:111], v[16:31]
	v_exp_f32_e32 v94, v94
	v_cvt_pk_bf16_f32 v102, v76, v77
	v_fmamk_f32 v79, v79, 0x3e16c740, v163
	ds_read_b64_tr_b16 v[188:189], v222 offset:6208
	ds_read_b64_tr_b16 v[190:191], v222 offset:7744
	s_waitcnt lgkmcnt(8)
	v_mfma_f32_32x32x16_bf16 v[48:63], v[148:151], v[132:135], v[48:63]
	v_fmamk_f32 v95, v95, 0x3e16c740, v163
	v_exp_f32_e32 v79, v79
	v_exp_f32_e32 v95, v95
	v_cvt_pk_bf16_f32 v103, v78, v79
	v_mfma_f32_32x32x16_bf16 v[226:241], v[246:249], v[108:111], v[226:241]
	v_cvt_pk_bf16_f32 v108, v88, v89
	v_cvt_pk_bf16_f32 v109, v90, v91
	v_cvt_pk_bf16_f32 v110, v92, v93
	v_cvt_pk_bf16_f32 v111, v94, v95
	s_cmp_lg_u32 s9, 0
	s_cbranch_scc0 .Lamla_noresc_7
	s_nop 15
	v_pk_mul_f32 v[0:1], v[0:1], v[166:167] op_sel_hi:[1,0]
	v_pk_mul_f32 v[2:3], v[2:3], v[166:167] op_sel_hi:[1,0]
	v_pk_mul_f32 v[4:5], v[4:5], v[166:167] op_sel_hi:[1,0]
	v_pk_mul_f32 v[6:7], v[6:7], v[166:167] op_sel_hi:[1,0]
	v_pk_mul_f32 v[8:9], v[8:9], v[166:167] op_sel_hi:[1,0]
	v_pk_mul_f32 v[10:11], v[10:11], v[166:167] op_sel_hi:[1,0]
	v_pk_mul_f32 v[12:13], v[12:13], v[166:167] op_sel_hi:[1,0]
	v_pk_mul_f32 v[14:15], v[14:15], v[166:167] op_sel_hi:[1,0]
	v_pk_mul_f32 v[16:17], v[16:17], v[166:167] op_sel_hi:[1,0]
	v_pk_mul_f32 v[18:19], v[18:19], v[166:167] op_sel_hi:[1,0]
	v_pk_mul_f32 v[20:21], v[20:21], v[166:167] op_sel_hi:[1,0]
	v_pk_mul_f32 v[22:23], v[22:23], v[166:167] op_sel_hi:[1,0]
	v_pk_mul_f32 v[24:25], v[24:25], v[166:167] op_sel_hi:[1,0]
	v_pk_mul_f32 v[26:27], v[26:27], v[166:167] op_sel_hi:[1,0]
	v_pk_mul_f32 v[28:29], v[28:29], v[166:167] op_sel_hi:[1,0]
	v_pk_mul_f32 v[30:31], v[30:31], v[166:167] op_sel_hi:[1,0]
	v_mul_f32_e32 v226, v226, v166
.Lamla_noresc_7:
	s_waitcnt lgkmcnt(0)
	s_barrier
	ds_read_b128 v[136:139], v243 offset:13312
	ds_read_b128 v[140:143], v243 offset:19968
	ds_read_b128 v[144:147], v243 offset:13344
	ds_read_b128 v[148:151], v243 offset:20000
	v_mfma_f32_32x32x16_bf16 v[0:15], v[176:179], v[96:99], v[0:15]
	v_max3_f32 v168, v32, v33, v34
	v_max3_f32 v170, v48, v49, v50
	v_max3_f32 v168, v168, v35, v36
	v_max3_f32 v170, v170, v51, v52
	v_max3_f32 v168, v168, v37, v38
	v_max3_f32 v170, v170, v53, v54
	s_mov_b32 s55, s52
	s_mov_b32 s52, s53
	s_mov_b32 s53, s54
	s_mov_b32 s54, s55
	s_mov_b32 s9, 0
	v_mfma_f32_32x32x16_bf16 v[16:31], v[180:183], v[96:99], v[16:31]
	v_max3_f32 v168, v168, v39, v40
	v_max3_f32 v170, v170, v55, v56
	v_max3_f32 v168, v168, v41, v42
	v_max3_f32 v170, v170, v57, v58
	v_max3_f32 v168, v168, v43, v44
	v_max3_f32 v170, v170, v59, v60
	v_add_u32_e32 v223, s53, v220
	v_add_u32_e32 v224, s54, v221
	v_mfma_f32_32x32x16_bf16 v[226:241], v[246:249], v[96:99], v[226:241]
	v_max3_f32 v168, v168, v45, v46
	v_max3_f32 v170, v170, v61, v62
	v_max_f32_e32 v168, v168, v47
	v_max_f32_e32 v170, v170, v63
	v_max_f32_e32 v168, v168, v170
	s_waitcnt lgkmcnt(3)
	v_mfma_f32_32x32x16_bf16 v[64:79], v[136:139], v[112:115], 0
	v_mov_b32_e32 v170, v168
	s_nop 1
	v_permlane32_swap_b32_e32 v168, v170
	v_max_f32_e32 v168, v168, v170
	v_mul_f32_e32 v168, 0x3e16c740, v168
	v_cmp_gt_f32_e32 vcc, v168, v164
	s_cbranch_vccz .Lamla_nors_8
	v_max_f32_e32 v170, v162, v168
	v_sub_f32_e32 v166, v162, v170
	v_exp_f32_e32 v166, v166
	v_mov_b32_e32 v162, v170
	v_add_f32_e32 v164, 0x41000000, v170
	v_xor_b32_e32 v163, 0x80000000, v170
	s_mov_b32 s9, 1
.Lamla_nors_8:
	ds_read_b128 v[136:139], v243 offset:13376
	ds_read_b64_tr_b16 v[192:193], v222 offset:3072
	ds_read_b64_tr_b16 v[194:195], v222 offset:4608
	s_waitcnt lgkmcnt(5)
	v_mfma_f32_32x32x16_bf16 v[80:95], v[140:143], v[112:115], 0
	v_fmamk_f32 v32, v32, 0x3e16c740, v163
	v_fmamk_f32 v48, v48, 0x3e16c740, v163
	v_exp_f32_e32 v32, v32
	v_exp_f32_e32 v48, v48
	ds_read_b128 v[140:143], v243 offset:20032
	ds_read_b64_tr_b16 v[196:197], v222 offset:3136
	ds_read_b64_tr_b16 v[198:199], v222 offset:4672
	v_mfma_f32_32x32x16_bf16 v[0:15], v[184:187], v[104:107], v[0:15]
	v_fmamk_f32 v33, v33, 0x3e16c740, v163
	v_fmamk_f32 v49, v49, 0x3e16c740, v163
	v_exp_f32_e32 v33, v33
	v_exp_f32_e32 v49, v49
	ds_read_b64_tr_b16 v[200:201], v222 offset:9216
	ds_read_b64_tr_b16 v[202:203], v222 offset:10752
	s_waitcnt lgkmcnt(9)
	v_mfma_f32_32x32x16_bf16 v[64:79], v[144:147], v[116:119], v[64:79]
	v_fmamk_f32 v34, v34, 0x3e16c740, v163
	v_fmamk_f32 v50, v50, 0x3e16c740, v163
	v_exp_f32_e32 v34, v34
	v_exp_f32_e32 v50, v50
	ds_read_b128 v[144:147], v243 offset:13408
	ds_read_b64_tr_b16 v[204:205], v222 offset:9280
	ds_read_b64_tr_b16 v[206:207], v222 offset:10816
	v_mfma_f32_32x32x16_bf16 v[16:31], v[188:191], v[104:107], v[16:31]
	v_cvt_pk_bf16_f32 v96, v32, v33
	v_fmamk_f32 v35, v35, 0x3e16c740, v163
	v_fmamk_f32 v51, v51, 0x3e16c740, v163
	v_exp_f32_e32 v35, v35
	s_waitcnt lgkmcnt(11)
	v_mfma_f32_32x32x16_bf16 v[80:95], v[148:151], v[116:119], v[80:95]
	v_exp_f32_e32 v51, v51
	v_fmamk_f32 v36, v36, 0x3e16c740, v163
	v_fmamk_f32 v52, v52, 0x3e16c740, v163
	v_exp_f32_e32 v36, v36
	ds_read_b128 v[148:151], v243 offset:20064
	v_mfma_f32_32x32x16_bf16 v[226:241], v[246:249], v[104:107], v[226:241]
	v_cvt_pk_bf16_f32 v104, v48, v49
	v_exp_f32_e32 v52, v52
	v_cvt_pk_bf16_f32 v97, v34, v35
	v_cvt_pk_bf16_f32 v105, v50, v51
	v_fmamk_f32 v37, v37, 0x3e16c740, v163
	s_waitcnt lgkmcnt(11)
	v_mfma_f32_32x32x16_bf16 v[64:79], v[136:139], v[120:123], v[64:79]
	v_fmamk_f32 v53, v53, 0x3e16c740, v163
	v_exp_f32_e32 v37, v37
	v_exp_f32_e32 v53, v53
	ds_read_b128 v[136:139], v243 offset:13440
	s_waitcnt lgkmcnt(9)
	v_mfma_f32_32x32x16_bf16 v[80:95], v[140:143], v[120:123], v[80:95]
	v_fmamk_f32 v38, v38, 0x3e16c740, v163
	v_fmamk_f32 v54, v54, 0x3e16c740, v163
	v_exp_f32_e32 v38, v38
	v_exp_f32_e32 v54, v54
	ds_read_b128 v[140:143], v243 offset:20096
	v_mfma_f32_32x32x16_bf16 v[0:15], v[192:195], v[100:103], v[0:15]
	v_cvt_pk_bf16_f32 v98, v36, v37
	v_cvt_pk_bf16_f32 v106, v52, v53
	v_fmamk_f32 v39, v39, 0x3e16c740, v163
	v_fmamk_f32 v55, v55, 0x3e16c740, v163
	v_exp_f32_e32 v39, v39
	s_waitcnt lgkmcnt(5)
	v_mfma_f32_32x32x16_bf16 v[64:79], v[144:147], v[124:127], v[64:79]
	v_exp_f32_e32 v55, v55
	v_fmamk_f32 v40, v40, 0x3e16c740, v163
	v_fmamk_f32 v56, v56, 0x3e16c740, v163
	v_exp_f32_e32 v40, v40
	ds_read_b128 v[144:147], v243 offset:13472
	v_mfma_f32_32x32x16_bf16 v[16:31], v[196:199], v[100:103], v[16:31]
	v_exp_f32_e32 v56, v56
	v_cvt_pk_bf16_f32 v99, v38, v39
	v_cvt_pk_bf16_f32 v107, v54, v55
	v_fmamk_f32 v41, v41, 0x3e16c740, v163
	s_waitcnt vmcnt(0)
	ds_write_b128 v224, v[156:159]
	s_waitcnt lgkmcnt(4)
	v_mfma_f32_32x32x16_bf16 v[80:95], v[148:151], v[124:127], v[80:95]
	v_fmamk_f32 v57, v57, 0x3e16c740, v163
	v_exp_f32_e32 v41, v41
	v_exp_f32_e32 v57, v57
	ds_read_b128 v[148:151], v243 offset:20128
	v_mfma_f32_32x32x16_bf16 v[226:241], v[246:249], v[100:103], v[226:241]
	v_fmamk_f32 v42, v42, 0x3e16c740, v163
	v_fmamk_f32 v58, v58, 0x3e16c740, v163
	v_exp_f32_e32 v42, v42
	v_exp_f32_e32 v58, v58
	s_waitcnt lgkmcnt(4)
	v_mfma_f32_32x32x16_bf16 v[64:79], v[136:139], v[128:131], v[64:79]
	v_cvt_pk_bf16_f32 v100, v40, v41
	v_fmamk_f32 v43, v43, 0x3e16c740, v163
	v_fmamk_f32 v59, v59, 0x3e16c740, v163
	v_exp_f32_e32 v43, v43
	v_exp_f32_e32 v59, v59
	s_waitcnt lgkmcnt(3)
	v_mfma_f32_32x32x16_bf16 v[80:95], v[140:143], v[128:131], v[80:95]
	v_fmamk_f32 v44, v44, 0x3e16c740, v163
	v_fmamk_f32 v60, v60, 0x3e16c740, v163
	v_exp_f32_e32 v44, v44
	ds_read_b64_tr_b16 v[176:177], v223 offset:0
	ds_read_b64_tr_b16 v[178:179], v223 offset:1536
	v_mfma_f32_32x32x16_bf16 v[0:15], v[200:203], v[108:111], v[0:15]
	v_exp_f32_e32 v60, v60
	v_cvt_pk_bf16_f32 v101, v42, v43
	v_fmamk_f32 v45, v45, 0x3e16c740, v163
	v_fmamk_f32 v61, v61, 0x3e16c740, v163
	v_exp_f32_e32 v45, v45
	ds_read_b64_tr_b16 v[180:181], v223 offset:64
	ds_read_b64_tr_b16 v[182:183], v223 offset:1600
	s_waitcnt lgkmcnt(6)
	v_mfma_f32_32x32x16_bf16 v[64:79], v[144:147], v[132:135], v[64:79]
	v_exp_f32_e32 v61, v61
	v_fmamk_f32 v46, v46, 0x3e16c740, v163
	v_fmamk_f32 v62, v62, 0x3e16c740, v163
	v_exp_f32_e32 v46, v46
	ds_read_b64_tr_b16 v[184:185], v223 offset:6144
	ds_read_b64_tr_b16 v[186:187], v223 offset:7680
	v_mfma_f32_32x32x16_bf16 v[16:31], v[204:207], v[108:111], v[16:31]
	v_exp_f32_e32 v62, v62
	v_cvt_pk_bf16_f32 v102, v44, v45
	v_fmamk_f32 v47, v47, 0x3e16c740, v163
	ds_read_b64_tr_b16 v[188:189], v223 offset:6208
	ds_read_b64_tr_b16 v[190:191], v223 offset:7744
	s_waitcnt lgkmcnt(8)
	v_mfma_f32_32x32x16_bf16 v[80:95], v[148:151], v[132:135], v[80:95]
	v_fmamk_f32 v63, v63, 0x3e16c740, v163
	v_exp_f32_e32 v47, v47
	v_exp_f32_e32 v63, v63
	v_cvt_pk_bf16_f32 v103, v46, v47
	v_mfma_f32_32x32x16_bf16 v[226:241], v[246:249], v[108:111], v[226:241]
	v_cvt_pk_bf16_f32 v108, v56, v57
	v_cvt_pk_bf16_f32 v109, v58, v59
	v_cvt_pk_bf16_f32 v110, v60, v61
	v_cvt_pk_bf16_f32 v111, v62, v63
	s_cmp_lg_u32 s9, 0
	s_cbranch_scc0 .Lamla_noresc_9
	s_nop 15
	v_pk_mul_f32 v[0:1], v[0:1], v[166:167] op_sel_hi:[1,0]
	v_pk_mul_f32 v[2:3], v[2:3], v[166:167] op_sel_hi:[1,0]
	v_pk_mul_f32 v[4:5], v[4:5], v[166:167] op_sel_hi:[1,0]
	v_pk_mul_f32 v[6:7], v[6:7], v[166:167] op_sel_hi:[1,0]
	v_pk_mul_f32 v[8:9], v[8:9], v[166:167] op_sel_hi:[1,0]
	v_pk_mul_f32 v[10:11], v[10:11], v[166:167] op_sel_hi:[1,0]
	v_pk_mul_f32 v[12:13], v[12:13], v[166:167] op_sel_hi:[1,0]
	v_pk_mul_f32 v[14:15], v[14:15], v[166:167] op_sel_hi:[1,0]
	v_pk_mul_f32 v[16:17], v[16:17], v[166:167] op_sel_hi:[1,0]
	v_pk_mul_f32 v[18:19], v[18:19], v[166:167] op_sel_hi:[1,0]
	v_pk_mul_f32 v[20:21], v[20:21], v[166:167] op_sel_hi:[1,0]
	v_pk_mul_f32 v[22:23], v[22:23], v[166:167] op_sel_hi:[1,0]
	v_pk_mul_f32 v[24:25], v[24:25], v[166:167] op_sel_hi:[1,0]
	v_pk_mul_f32 v[26:27], v[26:27], v[166:167] op_sel_hi:[1,0]
	v_pk_mul_f32 v[28:29], v[28:29], v[166:167] op_sel_hi:[1,0]
	v_pk_mul_f32 v[30:31], v[30:31], v[166:167] op_sel_hi:[1,0]
	v_mul_f32_e32 v226, v226, v166

.Lagqa_loop:
	ds_read_b128 v[136:139], v243 offset:0
	ds_read_b128 v[140:143], v243 offset:4608
	ds_read_b128 v[144:147], v243 offset:32
	ds_read_b128 v[148:151], v243 offset:4640
	v_mfma_f32_32x32x16_bf16 v[0:15], v[176:179], v[96:99], v[0:15]
	v_max3_f32 v168, v64, v65, v66
	v_max3_f32 v170, v80, v81, v82
	v_max3_f32 v168, v168, v67, v68
	v_max3_f32 v170, v170, v83, v84
	v_max3_f32 v168, v168, v69, v70
	v_max3_f32 v170, v170, v85, v86
	v_max3_f32 v168, v168, v71, v72
	s_mov_b32 s55, s52
	s_mov_b32 s52, s53
	s_mov_b32 s53, s54
	s_mov_b32 s54, s55
	s_mov_b32 s9, 0
	v_mfma_f32_32x32x16_bf16 v[16:31], v[180:183], v[96:99], v[16:31]
	v_max3_f32 v170, v170, v87, v88
	v_max3_f32 v168, v168, v73, v74
	v_max3_f32 v170, v170, v89, v90
	v_max3_f32 v168, v168, v75, v76
	v_max3_f32 v170, v170, v91, v92
	v_max3_f32 v168, v168, v77, v78
	v_max3_f32 v170, v170, v93, v94
	global_load_dwordx4 v[152:155], v225, s[2:3]
	global_load_dwordx4 v[156:159], v225, s[4:5]
	s_add_u32 s2, s2, 0x2000
	s_addc_u32 s3, s3, 0
	s_add_u32 s4, s4, 0x2000
	s_addc_u32 s5, s5, 0
	v_add_u32_e32 v222, s53, v220
	v_add_u32_e32 v224, s54, v221
	v_mfma_f32_32x32x16_bf16 v[226:241], v[246:249], v[96:99], v[226:241]
	v_max_f32_e32 v168, v168, v79
	v_max_f32_e32 v170, v170, v95
	v_max_f32_e32 v168, v168, v170
	v_mov_b32_e32 v170, v168
	s_nop 1
	v_permlane32_swap_b32_e32 v168, v170
	v_max_f32_e32 v168, v168, v170
	v_mul_f32_e32 v168, 0x3e38aa3b, v168
	s_waitcnt lgkmcnt(3)
	v_mfma_f32_32x32x16_bf16 v[32:47], v[136:139], v[112:115], 0
	v_cmp_gt_f32_e32 vcc, v168, v164
	s_cbranch_vccz .Lagqa_nors_2
	v_max_f32_e32 v170, v162, v168
	v_sub_f32_e32 v166, v162, v170
	v_exp_f32_e32 v166, v166
	v_mov_b32_e32 v162, v170
	v_add_f32_e32 v164, 0x41000000, v170
	v_xor_b32_e32 v163, 0x80000000, v170
	s_mov_b32 s9, 1
.Lagqa_nors_2:
	v_fmamk_f32 v64, v64, 0x3e38aa3b, v163
	v_fmamk_f32 v80, v80, 0x3e38aa3b, v163
	v_exp_f32_e32 v64, v64
	ds_read_b128 v[136:139], v243 offset:64
	ds_read_b64_tr_b16 v[192:193], v223 offset:3072
	ds_read_b64_tr_b16 v[194:195], v223 offset:4608
	v_mfma_f32_32x32x16_bf16 v[0:15], v[184:187], v[104:107], v[0:15]
	v_exp_f32_e32 v80, v80
	v_fmamk_f32 v65, v65, 0x3e38aa3b, v163
	v_fmamk_f32 v81, v81, 0x3e38aa3b, v163
	v_exp_f32_e32 v65, v65
	v_exp_f32_e32 v81, v81
	ds_read_b64_tr_b16 v[196:197], v223 offset:3136
	ds_read_b64_tr_b16 v[198:199], v223 offset:4672
	s_waitcnt lgkmcnt(7)
	v_mfma_f32_32x32x16_bf16 v[48:63], v[140:143], v[112:115], 0
	v_fmamk_f32 v66, v66, 0x3e38aa3b, v163
	v_fmamk_f32 v82, v82, 0x3e38aa3b, v163
	v_exp_f32_e32 v66, v66
	v_exp_f32_e32 v82, v82
	ds_read_b128 v[140:143], v243 offset:4672
	ds_read_b64_tr_b16 v[200:201], v223 offset:9216
	ds_read_b64_tr_b16 v[202:203], v223 offset:10752
	v_mfma_f32_32x32x16_bf16 v[16:31], v[188:191], v[104:107], v[16:31]
	v_cvt_pk_bf16_f32 v96, v64, v65
	v_fmamk_f32 v67, v67, 0x3e38aa3b, v163
	v_fmamk_f32 v83, v83, 0x3e38aa3b, v163
	v_exp_f32_e32 v67, v67
	v_exp_f32_e32 v83, v83
	ds_read_b64_tr_b16 v[204:205], v223 offset:9280
	ds_read_b64_tr_b16 v[206:207], v223 offset:10816
	s_waitcnt lgkmcnt(11)
	v_mfma_f32_32x32x16_bf16 v[32:47], v[144:147], v[116:119], v[32:47]
	v_fmamk_f32 v68, v68, 0x3e38aa3b, v163
	v_fmamk_f32 v84, v84, 0x3e38aa3b, v163
	v_exp_f32_e32 v68, v68
	v_exp_f32_e32 v84, v84
	ds_read_b128 v[144:147], v243 offset:96
	v_mfma_f32_32x32x16_bf16 v[226:241], v[246:249], v[104:107], v[226:241]
	v_cvt_pk_bf16_f32 v104, v80, v81
	v_cvt_pk_bf16_f32 v97, v66, v67
	v_cvt_pk_bf16_f32 v105, v82, v83
	v_fmamk_f32 v69, v69, 0x3e38aa3b, v163
	v_fmamk_f32 v85, v85, 0x3e38aa3b, v163
	v_exp_f32_e32 v69, v69
	v_exp_f32_e32 v85, v85
	s_waitcnt lgkmcnt(11)
	v_mfma_f32_32x32x16_bf16 v[48:63], v[148:151], v[116:119], v[48:63]
	v_fmamk_f32 v70, v70, 0x3e38aa3b, v163
	v_fmamk_f32 v86, v86, 0x3e38aa3b, v163
	v_exp_f32_e32 v70, v70
	v_exp_f32_e32 v86, v86
	ds_read_b128 v[148:151], v243 offset:4704
	s_waitcnt lgkmcnt(9)
	v_mfma_f32_32x32x16_bf16 v[0:15], v[192:195], v[100:103], v[0:15]
	v_cvt_pk_bf16_f32 v98, v68, v69
	v_cvt_pk_bf16_f32 v106, v84, v85
	v_fmamk_f32 v71, v71, 0x3e38aa3b, v163
	v_fmamk_f32 v87, v87, 0x3e38aa3b, v163
	v_exp_f32_e32 v71, v71
	v_exp_f32_e32 v87, v87
	v_mfma_f32_32x32x16_bf16 v[32:47], v[136:139], v[120:123], v[32:47]
	v_fmamk_f32 v72, v72, 0x3e38aa3b, v163
	v_fmamk_f32 v88, v88, 0x3e38aa3b, v163
	v_exp_f32_e32 v72, v72
	v_exp_f32_e32 v88, v88
	s_waitcnt vmcnt(3)
	ds_write_b128 v218, v[208:211] offset:9216
	s_waitcnt vmcnt(2)
	ds_write_b128 v224, v[212:215]
	s_waitcnt lgkmcnt(9)
	v_mfma_f32_32x32x16_bf16 v[16:31], v[196:199], v[100:103], v[16:31]
	v_cvt_pk_bf16_f32 v99, v70, v71
	v_cvt_pk_bf16_f32 v107, v86, v87
	v_fmamk_f32 v73, v73, 0x3e38aa3b, v163
	v_fmamk_f32 v89, v89, 0x3e38aa3b, v163
	v_exp_f32_e32 v73, v73
	s_waitcnt lgkmcnt(8)
	v_mfma_f32_32x32x16_bf16 v[48:63], v[140:143], v[120:123], v[48:63]
	v_exp_f32_e32 v89, v89
	v_fmamk_f32 v74, v74, 0x3e38aa3b, v163
	v_fmamk_f32 v90, v90, 0x3e38aa3b, v163
	v_exp_f32_e32 v74, v74
	v_exp_f32_e32 v90, v90
	v_mfma_f32_32x32x16_bf16 v[226:241], v[246:249], v[100:103], v[226:241]
	v_cvt_pk_bf16_f32 v100, v72, v73
	v_fmamk_f32 v75, v75, 0x3e38aa3b, v163
	v_fmamk_f32 v91, v91, 0x3e38aa3b, v163
	v_exp_f32_e32 v75, v75
	v_exp_f32_e32 v91, v91
	ds_read_b64_tr_b16 v[176:177], v222 offset:0
	ds_read_b64_tr_b16 v[178:179], v222 offset:1536
	s_waitcnt lgkmcnt(5)
	v_mfma_f32_32x32x16_bf16 v[32:47], v[144:147], v[124:127], v[32:47]
	v_fmamk_f32 v76, v76, 0x3e38aa3b, v163
	v_fmamk_f32 v92, v92, 0x3e38aa3b, v163
	v_exp_f32_e32 v76, v76
	v_exp_f32_e32 v92, v92
	ds_read_b64_tr_b16 v[180:181], v222 offset:64
	ds_read_b64_tr_b16 v[182:183], v222 offset:1600
	v_mfma_f32_32x32x16_bf16 v[0:15], v[200:203], v[108:111], v[0:15]
	v_cvt_pk_bf16_f32 v101, v74, v75
	v_fmamk_f32 v77, v77, 0x3e38aa3b, v163
	v_fmamk_f32 v93, v93, 0x3e38aa3b, v163
	v_exp_f32_e32 v77, v77
	v_exp_f32_e32 v93, v93
	ds_read_b64_tr_b16 v[184:185], v222 offset:6144
	ds_read_b64_tr_b16 v[186:187], v222 offset:7680
	s_waitcnt lgkmcnt(8)
	v_mfma_f32_32x32x16_bf16 v[48:63], v[148:151], v[124:127], v[48:63]
	v_fmamk_f32 v78, v78, 0x3e38aa3b, v163
	v_fmamk_f32 v94, v94, 0x3e38aa3b, v163
	v_exp_f32_e32 v78, v78
	v_exp_f32_e32 v94, v94
	ds_read_b64_tr_b16 v[188:189], v222 offset:6208
	ds_read_b64_tr_b16 v[190:191], v222 offset:7744
	v_mfma_f32_32x32x16_bf16 v[16:31], v[204:207], v[108:111], v[16:31]
	v_cvt_pk_bf16_f32 v102, v76, v77
	v_fmamk_f32 v79, v79, 0x3e38aa3b, v163
	v_fmamk_f32 v95, v95, 0x3e38aa3b, v163
	v_exp_f32_e32 v79, v79
	v_exp_f32_e32 v95, v95
	v_mfma_f32_32x32x16_bf16 v[226:241], v[246:249], v[108:111], v[226:241]
	v_cvt_pk_bf16_f32 v108, v88, v89
	v_cvt_pk_bf16_f32 v109, v90, v91
	v_cvt_pk_bf16_f32 v110, v92, v93
	v_cvt_pk_bf16_f32 v103, v78, v79
	v_cvt_pk_bf16_f32 v111, v94, v95
	s_cmp_lg_u32 s9, 0
	s_cbranch_scc0 .Lagqa_noresc_3
	s_nop 15
	v_pk_mul_f32 v[0:1], v[0:1], v[166:167] op_sel_hi:[1,0]
	v_pk_mul_f32 v[2:3], v[2:3], v[166:167] op_sel_hi:[1,0]
	v_pk_mul_f32 v[4:5], v[4:5], v[166:167] op_sel_hi:[1,0]
	v_pk_mul_f32 v[6:7], v[6:7], v[166:167] op_sel_hi:[1,0]
	v_pk_mul_f32 v[8:9], v[8:9], v[166:167] op_sel_hi:[1,0]
	v_pk_mul_f32 v[10:11], v[10:11], v[166:167] op_sel_hi:[1,0]
	v_pk_mul_f32 v[12:13], v[12:13], v[166:167] op_sel_hi:[1,0]
	v_pk_mul_f32 v[14:15], v[14:15], v[166:167] op_sel_hi:[1,0]
	v_pk_mul_f32 v[16:17], v[16:17], v[166:167] op_sel_hi:[1,0]
	v_pk_mul_f32 v[18:19], v[18:19], v[166:167] op_sel_hi:[1,0]
	v_pk_mul_f32 v[20:21], v[20:21], v[166:167] op_sel_hi:[1,0]
	v_pk_mul_f32 v[22:23], v[22:23], v[166:167] op_sel_hi:[1,0]
	v_pk_mul_f32 v[24:25], v[24:25], v[166:167] op_sel_hi:[1,0]
	v_pk_mul_f32 v[26:27], v[26:27], v[166:167] op_sel_hi:[1,0]
	v_pk_mul_f32 v[28:29], v[28:29], v[166:167] op_sel_hi:[1,0]
	v_pk_mul_f32 v[30:31], v[30:31], v[166:167] op_sel_hi:[1,0]
	v_mul_f32_e32 v226, v226, v166
.Lagqa_noresc_3:
	s_waitcnt lgkmcnt(0)
	s_barrier
	ds_read_b128 v[136:139], v243 offset:9216
	ds_read_b128 v[140:143], v243 offset:13824
	ds_read_b128 v[144:147], v243 offset:9248
	ds_read_b128 v[148:151], v243 offset:13856
	v_mfma_f32_32x32x16_bf16 v[0:15], v[176:179], v[96:99], v[0:15]
	v_max3_f32 v168, v32, v33, v34
	v_max3_f32 v170, v48, v49, v50
	v_max3_f32 v168, v168, v35, v36
	v_max3_f32 v170, v170, v51, v52
	v_max3_f32 v168, v168, v37, v38
	v_max3_f32 v170, v170, v53, v54
	v_max3_f32 v168, v168, v39, v40
	s_mov_b32 s55, s52
	s_mov_b32 s52, s53
	s_mov_b32 s53, s54
	s_mov_b32 s54, s55
	s_mov_b32 s9, 0
	v_mfma_f32_32x32x16_bf16 v[16:31], v[180:183], v[96:99], v[16:31]
	v_max3_f32 v170, v170, v55, v56
	v_max3_f32 v168, v168, v41, v42
	v_max3_f32 v170, v170, v57, v58
	v_max3_f32 v168, v168, v43, v44
	v_max3_f32 v170, v170, v59, v60
	v_max3_f32 v168, v168, v45, v46
	v_max3_f32 v170, v170, v61, v62
	global_load_dwordx4 v[208:211], v225, s[2:3]
	global_load_dwordx4 v[212:215], v225, s[4:5]
	s_add_u32 s2, s2, 0x2000
	s_addc_u32 s3, s3, 0
	s_add_u32 s4, s4, 0x2000
	s_addc_u32 s5, s5, 0
	v_add_u32_e32 v223, s53, v220
	v_add_u32_e32 v224, s54, v221
	v_mfma_f32_32x32x16_bf16 v[226:241], v[246:249], v[96:99], v[226:241]
	v_max_f32_e32 v168, v168, v47
	v_max_f32_e32 v170, v170, v63
	v_max_f32_e32 v168, v168, v170
	v_mov_b32_e32 v170, v168
	s_nop 1
	v_permlane32_swap_b32_e32 v168, v170
	v_max_f32_e32 v168, v168, v170
	v_mul_f32_e32 v168, 0x3e38aa3b, v168
	s_waitcnt lgkmcnt(3)
	v_mfma_f32_32x32x16_bf16 v[64:79], v[136:139], v[112:115], 0
	v_cmp_gt_f32_e32 vcc, v168, v164
	s_cbranch_vccz .Lagqa_nors_4
	v_max_f32_e32 v170, v162, v168
	v_sub_f32_e32 v166, v162, v170
	v_exp_f32_e32 v166, v166
	v_mov_b32_e32 v162, v170
	v_add_f32_e32 v164, 0x41000000, v170
	v_xor_b32_e32 v163, 0x80000000, v170
	s_mov_b32 s9, 1
.Lagqa_nors_4:
	v_fmamk_f32 v32, v32, 0x3e38aa3b, v163
	v_fmamk_f32 v48, v48, 0x3e38aa3b, v163
	v_exp_f32_e32 v32, v32
	ds_read_b128 v[136:139], v243 offset:9280
	ds_read_b64_tr_b16 v[192:193], v222 offset:3072
	ds_read_b64_tr_b16 v[194:195], v222 offset:4608
	v_mfma_f32_32x32x16_bf16 v[0:15], v[184:187], v[104:107], v[0:15]
	v_exp_f32_e32 v48, v48
	v_fmamk_f32 v33, v33, 0x3e38aa3b, v163
	v_fmamk_f32 v49, v49, 0x3e38aa3b, v163
	v_exp_f32_e32 v33, v33
	v_exp_f32_e32 v49, v49
	ds_read_b64_tr_b16 v[196:197], v222 offset:3136
	ds_read_b64_tr_b16 v[198:199], v222 offset:4672
	s_waitcnt lgkmcnt(7)
	v_mfma_f32_32x32x16_bf16 v[80:95], v[140:143], v[112:115], 0
	v_fmamk_f32 v34, v34, 0x3e38aa3b, v163
	v_fmamk_f32 v50, v50, 0x3e38aa3b, v163
	v_exp_f32_e32 v34, v34
	v_exp_f32_e32 v50, v50
	ds_read_b128 v[140:143], v243 offset:13888
	ds_read_b64_tr_b16 v[200:201], v222 offset:9216
	ds_read_b64_tr_b16 v[202:203], v222 offset:10752
	v_mfma_f32_32x32x16_bf16 v[16:31], v[188:191], v[104:107], v[16:31]
	v_cvt_pk_bf16_f32 v96, v32, v33
	v_fmamk_f32 v35, v35, 0x3e38aa3b, v163
	v_fmamk_f32 v51, v51, 0x3e38aa3b, v163
	v_exp_f32_e32 v35, v35
	v_exp_f32_e32 v51, v51
	ds_read_b64_tr_b16 v[204:205], v222 offset:9280
	ds_read_b64_tr_b16 v[206:207], v222 offset:10816
	s_waitcnt lgkmcnt(11)
	v_mfma_f32_32x32x16_bf16 v[64:79], v[144:147], v[116:119], v[64:79]
	v_fmamk_f32 v36, v36, 0x3e38aa3b, v163
	v_fmamk_f32 v52, v52, 0x3e38aa3b, v163
	v_exp_f32_e32 v36, v36
	v_exp_f32_e32 v52, v52
	ds_read_b128 v[144:147], v243 offset:9312
	v_mfma_f32_32x32x16_bf16 v[226:241], v[246:249], v[104:107], v[226:241]
	v_cvt_pk_bf16_f32 v104, v48, v49
	v_cvt_pk_bf16_f32 v97, v34, v35
	v_cvt_pk_bf16_f32 v105, v50, v51
	v_fmamk_f32 v37, v37, 0x3e38aa3b, v163
	v_fmamk_f32 v53, v53, 0x3e38aa3b, v163
	v_exp_f32_e32 v37, v37
	v_exp_f32_e32 v53, v53
	s_waitcnt lgkmcnt(11)
	v_mfma_f32_32x32x16_bf16 v[80:95], v[148:151], v[116:119], v[80:95]
	v_fmamk_f32 v38, v38, 0x3e38aa3b, v163
	v_fmamk_f32 v54, v54, 0x3e38aa3b, v163
	v_exp_f32_e32 v38, v38
	v_exp_f32_e32 v54, v54
	ds_read_b128 v[148:151], v243 offset:13920
	s_waitcnt lgkmcnt(9)
	v_mfma_f32_32x32x16_bf16 v[0:15], v[192:195], v[100:103], v[0:15]
	v_cvt_pk_bf16_f32 v98, v36, v37
	v_cvt_pk_bf16_f32 v106, v52, v53
	v_fmamk_f32 v39, v39, 0x3e38aa3b, v163
	v_fmamk_f32 v55, v55, 0x3e38aa3b, v163
	v_exp_f32_e32 v39, v39
	v_exp_f32_e32 v55, v55
	v_mfma_f32_32x32x16_bf16 v[64:79], v[136:139], v[120:123], v[64:79]
	v_fmamk_f32 v40, v40, 0x3e38aa3b, v163
	v_fmamk_f32 v56, v56, 0x3e38aa3b, v163
	v_exp_f32_e32 v40, v40
	v_exp_f32_e32 v56, v56
	s_waitcnt vmcnt(3)
	ds_write_b128 v218, v[152:155]
	s_waitcnt vmcnt(2)
	ds_write_b128 v224, v[156:159]
	s_waitcnt lgkmcnt(9)
	v_mfma_f32_32x32x16_bf16 v[16:31], v[196:199], v[100:103], v[16:31]
	v_cvt_pk_bf16_f32 v99, v38, v39
	v_cvt_pk_bf16_f32 v107, v54, v55
	v_fmamk_f32 v41, v41, 0x3e38aa3b, v163
	v_fmamk_f32 v57, v57, 0x3e38aa3b, v163
	v_exp_f32_e32 v41, v41
	s_waitcnt lgkmcnt(8)
	v_mfma_f32_32x32x16_bf16 v[80:95], v[140:143], v[120:123], v[80:95]
	v_exp_f32_e32 v57, v57
	v_fmamk_f32 v42, v42, 0x3e38aa3b, v163
	v_fmamk_f32 v58, v58, 0x3e38aa3b, v163
	v_exp_f32_e32 v42, v42
	v_exp_f32_e32 v58, v58
	v_mfma_f32_32x32x16_bf16 v[226:241], v[246:249], v[100:103], v[226:241]
	v_cvt_pk_bf16_f32 v100, v40, v41
	v_fmamk_f32 v43, v43, 0x3e38aa3b, v163
	v_fmamk_f32 v59, v59, 0x3e38aa3b, v163
	v_exp_f32_e32 v43, v43
	v_exp_f32_e32 v59, v59
	ds_read_b64_tr_b16 v[176:177], v223 offset:0
	ds_read_b64_tr_b16 v[178:179], v223 offset:1536
	s_waitcnt lgkmcnt(5)
	v_mfma_f32_32x32x16_bf16 v[64:79], v[144:147], v[124:127], v[64:79]
	v_fmamk_f32 v44, v44, 0x3e38aa3b, v163
	v_fmamk_f32 v60, v60, 0x3e38aa3b, v163
	v_exp_f32_e32 v44, v44
	v_exp_f32_e32 v60, v60
	ds_read_b64_tr_b16 v[180:181], v223 offset:64
	ds_read_b64_tr_b16 v[182:183], v223 offset:1600
	v_mfma_f32_32x32x16_bf16 v[0:15], v[200:203], v[108:111], v[0:15]
	v_cvt_pk_bf16_f32 v101, v42, v43
	v_fmamk_f32 v45, v45, 0x3e38aa3b, v163
	v_fmamk_f32 v61, v61, 0x3e38aa3b, v163
	v_exp_f32_e32 v45, v45
	v_exp_f32_e32 v61, v61
	ds_read_b64_tr_b16 v[184:185], v223 offset:6144
	ds_read_b64_tr_b16 v[186:187], v223 offset:7680
	s_waitcnt lgkmcnt(8)
	v_mfma_f32_32x32x16_bf16 v[80:95], v[148:151], v[124:127], v[80:95]
	v_fmamk_f32 v46, v46, 0x3e38aa3b, v163
	v_fmamk_f32 v62, v62, 0x3e38aa3b, v163
	v_exp_f32_e32 v46, v46
	v_exp_f32_e32 v62, v62
	ds_read_b64_tr_b16 v[188:189], v223 offset:6208
	ds_read_b64_tr_b16 v[190:191], v223 offset:7744
	v_mfma_f32_32x32x16_bf16 v[16:31], v[204:207], v[108:111], v[16:31]
	v_cvt_pk_bf16_f32 v102, v44, v45
	v_fmamk_f32 v47, v47, 0x3e38aa3b, v163
	v_fmamk_f32 v63, v63, 0x3e38aa3b, v163
	v_exp_f32_e32 v47, v47
	v_exp_f32_e32 v63, v63
	v_mfma_f32_32x32x16_bf16 v[226:241], v[246:249], v[108:111], v[226:241]
	v_cvt_pk_bf16_f32 v108, v56, v57
	v_cvt_pk_bf16_f32 v109, v58, v59
	v_cvt_pk_bf16_f32 v110, v60, v61
	v_cvt_pk_bf16_f32 v103, v46, v47
	v_cvt_pk_bf16_f32 v111, v62, v63
	s_cmp_lg_u32 s9, 0
	s_cbranch_scc0 .Lagqa_noresc_5
	s_nop 15
	v_pk_mul_f32 v[0:1], v[0:1], v[166:167] op_sel_hi:[1,0]
	v_pk_mul_f32 v[2:3], v[2:3], v[166:167] op_sel_hi:[1,0]
	v_pk_mul_f32 v[4:5], v[4:5], v[166:167] op_sel_hi:[1,0]
	v_pk_mul_f32 v[6:7], v[6:7], v[166:167] op_sel_hi:[1,0]
	v_pk_mul_f32 v[8:9], v[8:9], v[166:167] op_sel_hi:[1,0]
	v_pk_mul_f32 v[10:11], v[10:11], v[166:167] op_sel_hi:[1,0]
	v_pk_mul_f32 v[12:13], v[12:13], v[166:167] op_sel_hi:[1,0]
	v_pk_mul_f32 v[14:15], v[14:15], v[166:167] op_sel_hi:[1,0]
	v_pk_mul_f32 v[16:17], v[16:17], v[166:167] op_sel_hi:[1,0]
	v_pk_mul_f32 v[18:19], v[18:19], v[166:167] op_sel_hi:[1,0]
	v_pk_mul_f32 v[20:21], v[20:21], v[166:167] op_sel_hi:[1,0]
	v_pk_mul_f32 v[22:23], v[22:23], v[166:167] op_sel_hi:[1,0]
	v_pk_mul_f32 v[24:25], v[24:25], v[166:167] op_sel_hi:[1,0]
	v_pk_mul_f32 v[26:27], v[26:27], v[166:167] op_sel_hi:[1,0]
	v_pk_mul_f32 v[28:29], v[28:29], v[166:167] op_sel_hi:[1,0]
	v_pk_mul_f32 v[30:31], v[30:31], v[166:167] op_sel_hi:[1,0]
	v_mul_f32_e32 v226, v226, v166

.Lagqa_tail:
	ds_read_b128 v[136:139], v243 offset:0
	ds_read_b128 v[140:143], v243 offset:4608
	ds_read_b128 v[144:147], v243 offset:32
	ds_read_b128 v[148:151], v243 offset:4640
	v_mfma_f32_32x32x16_bf16 v[0:15], v[176:179], v[96:99], v[0:15]
	v_max3_f32 v168, v64, v65, v66
	v_max3_f32 v170, v80, v81, v82
	v_max3_f32 v168, v168, v67, v68
	v_max3_f32 v170, v170, v83, v84
	v_max3_f32 v168, v168, v69, v70
	v_max3_f32 v170, v170, v85, v86
	v_max3_f32 v168, v168, v71, v72
	s_mov_b32 s55, s52
	s_mov_b32 s52, s53
	s_mov_b32 s53, s54
	s_mov_b32 s54, s55
	s_mov_b32 s9, 0
	v_mfma_f32_32x32x16_bf16 v[16:31], v[180:183], v[96:99], v[16:31]
	v_max3_f32 v170, v170, v87, v88
	v_max3_f32 v168, v168, v73, v74
	v_max3_f32 v170, v170, v89, v90
	v_max3_f32 v168, v168, v75, v76
	v_max3_f32 v170, v170, v91, v92
	v_max3_f32 v168, v168, v77, v78
	v_max3_f32 v170, v170, v93, v94
	global_load_dwordx4 v[156:159], v225, s[4:5]
	s_add_u32 s4, s4, 0x2000
	s_addc_u32 s5, s5, 0
	v_add_u32_e32 v222, s53, v220
	v_add_u32_e32 v224, s54, v221
	v_mfma_f32_32x32x16_bf16 v[226:241], v[246:249], v[96:99], v[226:241]
	v_max_f32_e32 v168, v168, v79
	v_max_f32_e32 v170, v170, v95
	v_max_f32_e32 v168, v168, v170
	v_mov_b32_e32 v170, v168
	s_nop 1
	v_permlane32_swap_b32_e32 v168, v170
	v_max_f32_e32 v168, v168, v170
	v_mul_f32_e32 v168, 0x3e38aa3b, v168
	s_waitcnt lgkmcnt(3)
	v_mfma_f32_32x32x16_bf16 v[32:47], v[136:139], v[112:115], 0
	v_cmp_gt_f32_e32 vcc, v168, v164
	s_cbranch_vccz .Lagqa_nors_6
	v_max_f32_e32 v170, v162, v168
	v_sub_f32_e32 v166, v162, v170
	v_exp_f32_e32 v166, v166
	v_mov_b32_e32 v162, v170
	v_add_f32_e32 v164, 0x41000000, v170
	v_xor_b32_e32 v163, 0x80000000, v170
	s_mov_b32 s9, 1
.Lagqa_nors_6:
	v_fmamk_f32 v64, v64, 0x3e38aa3b, v163
	v_fmamk_f32 v80, v80, 0x3e38aa3b, v163
	v_exp_f32_e32 v64, v64
	ds_read_b128 v[136:139], v243 offset:64
	ds_read_b64_tr_b16 v[192:193], v223 offset:3072
	ds_read_b64_tr_b16 v[194:195], v223 offset:4608
	v_mfma_f32_32x32x16_bf16 v[0:15], v[184:187], v[104:107], v[0:15]
	v_exp_f32_e32 v80, v80
	v_fmamk_f32 v65, v65, 0x3e38aa3b, v163
	v_fmamk_f32 v81, v81, 0x3e38aa3b, v163
	v_exp_f32_e32 v65, v65
	v_exp_f32_e32 v81, v81
	ds_read_b64_tr_b16 v[196:197], v223 offset:3136
	ds_read_b64_tr_b16 v[198:199], v223 offset:4672
	s_waitcnt lgkmcnt(7)
	v_mfma_f32_32x32x16_bf16 v[48:63], v[140:143], v[112:115], 0
	v_fmamk_f32 v66, v66, 0x3e38aa3b, v163
	v_fmamk_f32 v82, v82, 0x3e38aa3b, v163
	v_exp_f32_e32 v66, v66
	v_exp_f32_e32 v82, v82
	ds_read_b128 v[140:143], v243 offset:4672
	ds_read_b64_tr_b16 v[200:201], v223 offset:9216
	ds_read_b64_tr_b16 v[202:203], v223 offset:10752
	v_mfma_f32_32x32x16_bf16 v[16:31], v[188:191], v[104:107], v[16:31]
	v_cvt_pk_bf16_f32 v96, v64, v65
	v_fmamk_f32 v67, v67, 0x3e38aa3b, v163
	v_fmamk_f32 v83, v83, 0x3e38aa3b, v163
	v_exp_f32_e32 v67, v67
	v_exp_f32_e32 v83, v83
	ds_read_b64_tr_b16 v[204:205], v223 offset:9280
	ds_read_b64_tr_b16 v[206:207], v223 offset:10816
	s_waitcnt lgkmcnt(11)
	v_mfma_f32_32x32x16_bf16 v[32:47], v[144:147], v[116:119], v[32:47]
	v_fmamk_f32 v68, v68, 0x3e38aa3b, v163
	v_fmamk_f32 v84, v84, 0x3e38aa3b, v163
	v_exp_f32_e32 v68, v68
	v_exp_f32_e32 v84, v84
	ds_read_b128 v[144:147], v243 offset:96
	v_mfma_f32_32x32x16_bf16 v[226:241], v[246:249], v[104:107], v[226:241]
	v_cvt_pk_bf16_f32 v104, v80, v81
	v_cvt_pk_bf16_f32 v97, v66, v67
	v_cvt_pk_bf16_f32 v105, v82, v83
	v_fmamk_f32 v69, v69, 0x3e38aa3b, v163
	v_fmamk_f32 v85, v85, 0x3e38aa3b, v163
	v_exp_f32_e32 v69, v69
	v_exp_f32_e32 v85, v85
	s_waitcnt lgkmcnt(11)
	v_mfma_f32_32x32x16_bf16 v[48:63], v[148:151], v[116:119], v[48:63]
	v_fmamk_f32 v70, v70, 0x3e38aa3b, v163
	v_fmamk_f32 v86, v86, 0x3e38aa3b, v163
	v_exp_f32_e32 v70, v70
	v_exp_f32_e32 v86, v86
	ds_read_b128 v[148:151], v243 offset:4704
	s_waitcnt lgkmcnt(9)
	v_mfma_f32_32x32x16_bf16 v[0:15], v[192:195], v[100:103], v[0:15]
	v_cvt_pk_bf16_f32 v98, v68, v69
	v_cvt_pk_bf16_f32 v106, v84, v85
	v_fmamk_f32 v71, v71, 0x3e38aa3b, v163
	v_fmamk_f32 v87, v87, 0x3e38aa3b, v163
	v_exp_f32_e32 v71, v71
	v_exp_f32_e32 v87, v87
	v_mfma_f32_32x32x16_bf16 v[32:47], v[136:139], v[120:123], v[32:47]
	v_fmamk_f32 v72, v72, 0x3e38aa3b, v163
	v_fmamk_f32 v88, v88, 0x3e38aa3b, v163
	v_exp_f32_e32 v72, v72
	v_exp_f32_e32 v88, v88
	s_waitcnt vmcnt(2)
	ds_write_b128 v218, v[208:211] offset:9216
	s_waitcnt vmcnt(1)
	ds_write_b128 v224, v[212:215]
	s_waitcnt lgkmcnt(9)
	v_mfma_f32_32x32x16_bf16 v[16:31], v[196:199], v[100:103], v[16:31]
	v_cvt_pk_bf16_f32 v99, v70, v71
	v_cvt_pk_bf16_f32 v107, v86, v87
	v_fmamk_f32 v73, v73, 0x3e38aa3b, v163
	v_fmamk_f32 v89, v89, 0x3e38aa3b, v163
	v_exp_f32_e32 v73, v73
	s_waitcnt lgkmcnt(8)
	v_mfma_f32_32x32x16_bf16 v[48:63], v[140:143], v[120:123], v[48:63]
	v_exp_f32_e32 v89, v89
	v_fmamk_f32 v74, v74, 0x3e38aa3b, v163
	v_fmamk_f32 v90, v90, 0x3e38aa3b, v163
	v_exp_f32_e32 v74, v74
	v_exp_f32_e32 v90, v90
	v_mfma_f32_32x32x16_bf16 v[226:241], v[246:249], v[100:103], v[226:241]
	v_cvt_pk_bf16_f32 v100, v72, v73
	v_fmamk_f32 v75, v75, 0x3e38aa3b, v163
	v_fmamk_f32 v91, v91, 0x3e38aa3b, v163
	v_exp_f32_e32 v75, v75
	v_exp_f32_e32 v91, v91
	ds_read_b64_tr_b16 v[176:177], v222 offset:0
	ds_read_b64_tr_b16 v[178:179], v222 offset:1536
	s_waitcnt lgkmcnt(5)
	v_mfma_f32_32x32x16_bf16 v[32:47], v[144:147], v[124:127], v[32:47]
	v_fmamk_f32 v76, v76, 0x3e38aa3b, v163
	v_fmamk_f32 v92, v92, 0x3e38aa3b, v163
	v_exp_f32_e32 v76, v76
	v_exp_f32_e32 v92, v92
	ds_read_b64_tr_b16 v[180:181], v222 offset:64
	ds_read_b64_tr_b16 v[182:183], v222 offset:1600
	v_mfma_f32_32x32x16_bf16 v[0:15], v[200:203], v[108:111], v[0:15]
	v_cvt_pk_bf16_f32 v101, v74, v75
	v_fmamk_f32 v77, v77, 0x3e38aa3b, v163
	v_fmamk_f32 v93, v93, 0x3e38aa3b, v163
	v_exp_f32_e32 v77, v77
	v_exp_f32_e32 v93, v93
	ds_read_b64_tr_b16 v[184:185], v222 offset:6144
	ds_read_b64_tr_b16 v[186:187], v222 offset:7680
	s_waitcnt lgkmcnt(8)
	v_mfma_f32_32x32x16_bf16 v[48:63], v[148:151], v[124:127], v[48:63]
	v_fmamk_f32 v78, v78, 0x3e38aa3b, v163
	v_fmamk_f32 v94, v94, 0x3e38aa3b, v163
	v_exp_f32_e32 v78, v78
	v_exp_f32_e32 v94, v94
	ds_read_b64_tr_b16 v[188:189], v222 offset:6208
	ds_read_b64_tr_b16 v[190:191], v222 offset:7744
	v_mfma_f32_32x32x16_bf16 v[16:31], v[204:207], v[108:111], v[16:31]
	v_cvt_pk_bf16_f32 v102, v76, v77
	v_fmamk_f32 v79, v79, 0x3e38aa3b, v163
	v_fmamk_f32 v95, v95, 0x3e38aa3b, v163
	v_exp_f32_e32 v79, v79
	v_exp_f32_e32 v95, v95
	v_mfma_f32_32x32x16_bf16 v[226:241], v[246:249], v[108:111], v[226:241]
	v_cvt_pk_bf16_f32 v108, v88, v89
	v_cvt_pk_bf16_f32 v109, v90, v91
	v_cvt_pk_bf16_f32 v110, v92, v93
	v_cvt_pk_bf16_f32 v103, v78, v79
	v_cvt_pk_bf16_f32 v111, v94, v95
	s_cmp_lg_u32 s9, 0
	s_cbranch_scc0 .Lagqa_noresc_7
	s_nop 15
	v_pk_mul_f32 v[0:1], v[0:1], v[166:167] op_sel_hi:[1,0]
	v_pk_mul_f32 v[2:3], v[2:3], v[166:167] op_sel_hi:[1,0]
	v_pk_mul_f32 v[4:5], v[4:5], v[166:167] op_sel_hi:[1,0]
	v_pk_mul_f32 v[6:7], v[6:7], v[166:167] op_sel_hi:[1,0]
	v_pk_mul_f32 v[8:9], v[8:9], v[166:167] op_sel_hi:[1,0]
	v_pk_mul_f32 v[10:11], v[10:11], v[166:167] op_sel_hi:[1,0]
	v_pk_mul_f32 v[12:13], v[12:13], v[166:167] op_sel_hi:[1,0]
	v_pk_mul_f32 v[14:15], v[14:15], v[166:167] op_sel_hi:[1,0]
	v_pk_mul_f32 v[16:17], v[16:17], v[166:167] op_sel_hi:[1,0]
	v_pk_mul_f32 v[18:19], v[18:19], v[166:167] op_sel_hi:[1,0]
	v_pk_mul_f32 v[20:21], v[20:21], v[166:167] op_sel_hi:[1,0]
	v_pk_mul_f32 v[22:23], v[22:23], v[166:167] op_sel_hi:[1,0]
	v_pk_mul_f32 v[24:25], v[24:25], v[166:167] op_sel_hi:[1,0]
	v_pk_mul_f32 v[26:27], v[26:27], v[166:167] op_sel_hi:[1,0]
	v_pk_mul_f32 v[28:29], v[28:29], v[166:167] op_sel_hi:[1,0]
	v_pk_mul_f32 v[30:31], v[30:31], v[166:167] op_sel_hi:[1,0]
	v_mul_f32_e32 v226, v226, v166
.Lagqa_noresc_7:
	s_waitcnt lgkmcnt(0)
	s_barrier
	ds_read_b128 v[136:139], v243 offset:9216
	ds_read_b128 v[140:143], v243 offset:13824
	ds_read_b128 v[144:147], v243 offset:9248
	ds_read_b128 v[148:151], v243 offset:13856
	v_mfma_f32_32x32x16_bf16 v[0:15], v[176:179], v[96:99], v[0:15]
	v_max3_f32 v168, v32, v33, v34
	v_max3_f32 v170, v48, v49, v50
	v_max3_f32 v168, v168, v35, v36
	v_max3_f32 v170, v170, v51, v52
	v_max3_f32 v168, v168, v37, v38
	v_max3_f32 v170, v170, v53, v54
	v_max3_f32 v168, v168, v39, v40
	s_mov_b32 s55, s52
	s_mov_b32 s52, s53
	s_mov_b32 s53, s54
	s_mov_b32 s54, s55
	s_mov_b32 s9, 0
	v_mfma_f32_32x32x16_bf16 v[16:31], v[180:183], v[96:99], v[16:31]
	v_max3_f32 v170, v170, v55, v56
	v_max3_f32 v168, v168, v41, v42
	v_max3_f32 v170, v170, v57, v58
	v_max3_f32 v168, v168, v43, v44
	v_max3_f32 v170, v170, v59, v60
	v_max3_f32 v168, v168, v45, v46
	v_max3_f32 v170, v170, v61, v62
	v_add_u32_e32 v223, s53, v220
	v_add_u32_e32 v224, s54, v221
	v_mfma_f32_32x32x16_bf16 v[226:241], v[246:249], v[96:99], v[226:241]
	v_max_f32_e32 v168, v168, v47
	v_max_f32_e32 v170, v170, v63
	v_max_f32_e32 v168, v168, v170
	v_mov_b32_e32 v170, v168
	s_nop 1
	v_permlane32_swap_b32_e32 v168, v170
	v_max_f32_e32 v168, v168, v170
	v_mul_f32_e32 v168, 0x3e38aa3b, v168
	s_waitcnt lgkmcnt(3)
	v_mfma_f32_32x32x16_bf16 v[64:79], v[136:139], v[112:115], 0
	v_cmp_gt_f32_e32 vcc, v168, v164
	s_cbranch_vccz .Lagqa_nors_8
	v_max_f32_e32 v170, v162, v168
	v_sub_f32_e32 v166, v162, v170
	v_exp_f32_e32 v166, v166
	v_mov_b32_e32 v162, v170
	v_add_f32_e32 v164, 0x41000000, v170
	v_xor_b32_e32 v163, 0x80000000, v170
	s_mov_b32 s9, 1
.Lagqa_nors_8:
	v_fmamk_f32 v32, v32, 0x3e38aa3b, v163
	v_fmamk_f32 v48, v48, 0x3e38aa3b, v163
	v_exp_f32_e32 v32, v32
	ds_read_b128 v[136:139], v243 offset:9280
	ds_read_b64_tr_b16 v[192:193], v222 offset:3072
	ds_read_b64_tr_b16 v[194:195], v222 offset:4608
	v_mfma_f32_32x32x16_bf16 v[0:15], v[184:187], v[104:107], v[0:15]
	v_exp_f32_e32 v48, v48
	v_fmamk_f32 v33, v33, 0x3e38aa3b, v163
	v_fmamk_f32 v49, v49, 0x3e38aa3b, v163
	v_exp_f32_e32 v33, v33
	v_exp_f32_e32 v49, v49
	ds_read_b64_tr_b16 v[196:197], v222 offset:3136
	ds_read_b64_tr_b16 v[198:199], v222 offset:4672
	s_waitcnt lgkmcnt(7)
	v_mfma_f32_32x32x16_bf16 v[80:95], v[140:143], v[112:115], 0
	v_fmamk_f32 v34, v34, 0x3e38aa3b, v163
	v_fmamk_f32 v50, v50, 0x3e38aa3b, v163
	v_exp_f32_e32 v34, v34
	v_exp_f32_e32 v50, v50
	ds_read_b128 v[140:143], v243 offset:13888
	ds_read_b64_tr_b16 v[200:201], v222 offset:9216
	ds_read_b64_tr_b16 v[202:203], v222 offset:10752
	v_mfma_f32_32x32x16_bf16 v[16:31], v[188:191], v[104:107], v[16:31]
	v_cvt_pk_bf16_f32 v96, v32, v33
	v_fmamk_f32 v35, v35, 0x3e38aa3b, v163
	v_fmamk_f32 v51, v51, 0x3e38aa3b, v163
	v_exp_f32_e32 v35, v35
	v_exp_f32_e32 v51, v51
	ds_read_b64_tr_b16 v[204:205], v222 offset:9280
	ds_read_b64_tr_b16 v[206:207], v222 offset:10816
	s_waitcnt lgkmcnt(11)
	v_mfma_f32_32x32x16_bf16 v[64:79], v[144:147], v[116:119], v[64:79]
	v_fmamk_f32 v36, v36, 0x3e38aa3b, v163
	v_fmamk_f32 v52, v52, 0x3e38aa3b, v163
	v_exp_f32_e32 v36, v36
	v_exp_f32_e32 v52, v52
	ds_read_b128 v[144:147], v243 offset:9312
	v_mfma_f32_32x32x16_bf16 v[226:241], v[246:249], v[104:107], v[226:241]
	v_cvt_pk_bf16_f32 v104, v48, v49
	v_cvt_pk_bf16_f32 v97, v34, v35
	v_cvt_pk_bf16_f32 v105, v50, v51
	v_fmamk_f32 v37, v37, 0x3e38aa3b, v163
	v_fmamk_f32 v53, v53, 0x3e38aa3b, v163
	v_exp_f32_e32 v37, v37
	v_exp_f32_e32 v53, v53
	s_waitcnt lgkmcnt(11)
	v_mfma_f32_32x32x16_bf16 v[80:95], v[148:151], v[116:119], v[80:95]
	v_fmamk_f32 v38, v38, 0x3e38aa3b, v163
	v_fmamk_f32 v54, v54, 0x3e38aa3b, v163
	v_exp_f32_e32 v38, v38
	v_exp_f32_e32 v54, v54
	ds_read_b128 v[148:151], v243 offset:13920
	s_waitcnt lgkmcnt(9)
	v_mfma_f32_32x32x16_bf16 v[0:15], v[192:195], v[100:103], v[0:15]
	v_cvt_pk_bf16_f32 v98, v36, v37
	v_cvt_pk_bf16_f32 v106, v52, v53
	v_fmamk_f32 v39, v39, 0x3e38aa3b, v163
	v_fmamk_f32 v55, v55, 0x3e38aa3b, v163
	v_exp_f32_e32 v39, v39
	v_exp_f32_e32 v55, v55
	v_mfma_f32_32x32x16_bf16 v[64:79], v[136:139], v[120:123], v[64:79]
	v_fmamk_f32 v40, v40, 0x3e38aa3b, v163
	v_fmamk_f32 v56, v56, 0x3e38aa3b, v163
	v_exp_f32_e32 v40, v40
	v_exp_f32_e32 v56, v56
	s_waitcnt vmcnt(0)
	ds_write_b128 v224, v[156:159]
	s_waitcnt lgkmcnt(8)
	v_mfma_f32_32x32x16_bf16 v[16:31], v[196:199], v[100:103], v[16:31]
	v_cvt_pk_bf16_f32 v99, v38, v39
	v_cvt_pk_bf16_f32 v107, v54, v55
	v_fmamk_f32 v41, v41, 0x3e38aa3b, v163
	v_fmamk_f32 v57, v57, 0x3e38aa3b, v163
	v_exp_f32_e32 v41, v41
	s_waitcnt lgkmcnt(7)
	v_mfma_f32_32x32x16_bf16 v[80:95], v[140:143], v[120:123], v[80:95]
	v_exp_f32_e32 v57, v57
	v_fmamk_f32 v42, v42, 0x3e38aa3b, v163
	v_fmamk_f32 v58, v58, 0x3e38aa3b, v163
	v_exp_f32_e32 v42, v42
	v_exp_f32_e32 v58, v58
	v_mfma_f32_32x32x16_bf16 v[226:241], v[246:249], v[100:103], v[226:241]
	v_cvt_pk_bf16_f32 v100, v40, v41
	v_fmamk_f32 v43, v43, 0x3e38aa3b, v163
	v_fmamk_f32 v59, v59, 0x3e38aa3b, v163
	v_exp_f32_e32 v43, v43
	v_exp_f32_e32 v59, v59
	ds_read_b64_tr_b16 v[176:177], v223 offset:0
	ds_read_b64_tr_b16 v[178:179], v223 offset:1536
	s_waitcnt lgkmcnt(4)
	v_mfma_f32_32x32x16_bf16 v[64:79], v[144:147], v[124:127], v[64:79]
	v_fmamk_f32 v44, v44, 0x3e38aa3b, v163
	v_fmamk_f32 v60, v60, 0x3e38aa3b, v163
	v_exp_f32_e32 v44, v44
	v_exp_f32_e32 v60, v60
	ds_read_b64_tr_b16 v[180:181], v223 offset:64
	ds_read_b64_tr_b16 v[182:183], v223 offset:1600
	v_mfma_f32_32x32x16_bf16 v[0:15], v[200:203], v[108:111], v[0:15]
	v_cvt_pk_bf16_f32 v101, v42, v43
	v_fmamk_f32 v45, v45, 0x3e38aa3b, v163
	v_fmamk_f32 v61, v61, 0x3e38aa3b, v163
	v_exp_f32_e32 v45, v45
	v_exp_f32_e32 v61, v61
	ds_read_b64_tr_b16 v[184:185], v223 offset:6144
	ds_read_b64_tr_b16 v[186:187], v223 offset:7680
	s_waitcnt lgkmcnt(7)
	v_mfma_f32_32x32x16_bf16 v[80:95], v[148:151], v[124:127], v[80:95]
	v_fmamk_f32 v46, v46, 0x3e38aa3b, v163
	v_fmamk_f32 v62, v62, 0x3e38aa3b, v163
	v_exp_f32_e32 v46, v46
	v_exp_f32_e32 v62, v62
	ds_read_b64_tr_b16 v[188:189], v223 offset:6208
	ds_read_b64_tr_b16 v[190:191], v223 offset:7744
	v_mfma_f32_32x32x16_bf16 v[16:31], v[204:207], v[108:111], v[16:31]
	v_cvt_pk_bf16_f32 v102, v44, v45
	v_fmamk_f32 v47, v47, 0x3e38aa3b, v163
	v_fmamk_f32 v63, v63, 0x3e38aa3b, v163
	v_exp_f32_e32 v47, v47
	v_exp_f32_e32 v63, v63
	v_mfma_f32_32x32x16_bf16 v[226:241], v[246:249], v[108:111], v[226:241]
	v_cvt_pk_bf16_f32 v108, v56, v57
	v_cvt_pk_bf16_f32 v109, v58, v59
	v_cvt_pk_bf16_f32 v110, v60, v61
	v_cvt_pk_bf16_f32 v103, v46, v47
	v_cvt_pk_bf16_f32 v111, v62, v63
	s_cmp_lg_u32 s9, 0
	s_cbranch_scc0 .Lagqa_noresc_9
	s_nop 15
	v_pk_mul_f32 v[0:1], v[0:1], v[166:167] op_sel_hi:[1,0]
	v_pk_mul_f32 v[2:3], v[2:3], v[166:167] op_sel_hi:[1,0]
	v_pk_mul_f32 v[4:5], v[4:5], v[166:167] op_sel_hi:[1,0]
	v_pk_mul_f32 v[6:7], v[6:7], v[166:167] op_sel_hi:[1,0]
	v_pk_mul_f32 v[8:9], v[8:9], v[166:167] op_sel_hi:[1,0]
	v_pk_mul_f32 v[10:11], v[10:11], v[166:167] op_sel_hi:[1,0]
	v_pk_mul_f32 v[12:13], v[12:13], v[166:167] op_sel_hi:[1,0]
	v_pk_mul_f32 v[14:15], v[14:15], v[166:167] op_sel_hi:[1,0]
	v_pk_mul_f32 v[16:17], v[16:17], v[166:167] op_sel_hi:[1,0]
	v_pk_mul_f32 v[18:19], v[18:19], v[166:167] op_sel_hi:[1,0]
	v_pk_mul_f32 v[20:21], v[20:21], v[166:167] op_sel_hi:[1,0]
	v_pk_mul_f32 v[22:23], v[22:23], v[166:167] op_sel_hi:[1,0]
	v_pk_mul_f32 v[24:25], v[24:25], v[166:167] op_sel_hi:[1,0]
	v_pk_mul_f32 v[26:27], v[26:27], v[166:167] op_sel_hi:[1,0]
	v_pk_mul_f32 v[28:29], v[28:29], v[166:167] op_sel_hi:[1,0]
	v_pk_mul_f32 v[30:31], v[30:31], v[166:167] op_sel_hi:[1,0]
	v_mul_f32_e32 v226, v226, v166
